# v18 + attention unit prologue load hoist + counted V-fragment wait before first PV MFMA + packed ReLU^2 squares in FF1 epilogues (all bit-identical)
# baseline (speedup 1.0000x reference)
; __device__ __forceinline__ u32x4 pack8(f32x4 v0, f32x4 v1) { u32x4 w; w.x = cvt_pk_bf16(v0[0], v0[1]); w.y = cvt_pk_bf16(v0[2], v0[3]); w.z = cvt_pk_bf16(v1[0], v1[1]); w.w = cvt_pk_bf16(v1[2], v1[3]); return w; }
; __device__ __forceinline__ float row_rstd16_q(const float* ssqx, int row, int fq) {
;     const f32x4 s0 = *(const f32x4*)(ssqx + (size_t)row * 16 + 4 * fq); float s = (s0[0] + s0[1]) + (s0[2] + s0[3]);
;     { auto r = __builtin_amdgcn_permlane16_swap(__float_as_uint(s), __float_as_uint(s), false, false); s = __uint_as_float(r[0]) + __uint_as_float(r[1]); }
;     { auto r = __builtin_amdgcn_permlane32_swap(__float_as_uint(s), __float_as_uint(s), false, false); s = __uint_as_float(r[0]) + __uint_as_float(r[1]); }
;     return rsqrtf(s * (1.0f / 1024.0f) + 1e-6f);
; }
;     __device__ __forceinline__ void operator()(const f32x4 (&acc)[2][2][4][2], const Unit& u, int wr, int wc, int fr, int fq) const {
;         const int row0 = row_base + u.pm * BM + wr * 64 + fr, col0 = u.pn * BM + wc * 32 + 8 * fq;
;         const int mi = (row_base + u.pm * BM >= T_LAT) ? 8 : ((row_base + u.pm * BM) >> 13);
;         f32x4 sw[2][2];
; #pragma unroll
;         for (int bj = 0; bj < 2; ++bj) { sw[bj][0] = *(const f32x4*)(shw + mi * 4096 + col0 + bj * HALF); sw[bj][1] = *(const f32x4*)(shw + mi * 4096 + col0 + bj * HALF + 4); }
;         float rsv[2][4];
; #pragma unroll
;         for (int ai = 0; ai < 2; ++ai) {
; #pragma unroll
;             for (int m = 0; m < 4; ++m) { rsv[ai][m] = row_rstd16_q(ssqx, row0 + ai * HALF + m * 16, fq); if (m & 1) asm volatile("" : "+v"(rsv[ai][m - 1]), "+v"(rsv[ai][m]) :: "memory"); } }
; #pragma unroll
;         for (int ai = 0; ai < 2; ++ai)
; #pragma unroll
;             for (int m = 0; m < 4; ++m) { const int row = row0 + ai * HALF + m * 16; bf16_t* rowp = H + (size_t)row * 4096 + col0; const float rs = rsv[ai][m];
; #pragma unroll
;                 for (int bj = 0; bj < 2; ++bj) { f32x4 v0 = acc[ai][bj][m][0] * rs + sw[bj][0], v1 = acc[ai][bj][m][1] * rs + sw[bj][1];
; #pragma unroll
;                     for (int e = 0; e < 4; ++e) { const float a = fmaxf(v0[e], 0.f), b = fmaxf(v1[e], 0.f); v0[e] = a * a; v1[e] = b * b; }
;                     *(u32x4*)(rowp + bj * HALF) = pack8(v0, v1); }
.LBB0_97:
	v_mbcnt_lo_u32_b32 v130, -1, 0
	v_mbcnt_hi_u32_b32 v130, -1, v130
	s_lshl_b32 s28, s97, 8
	v_ashrrev_i32_e32 v138, 4, v130
	s_add_i32 s28, s28, 0x10000
	v_and_or_b32 v130, v130, 15, s20
	v_add_u32_e32 v172, s28, v130
	v_lshlrev_b32_e32 v130, 2, v138
	v_ashrrev_i32_e32 v173, 31, v172
	v_ashrrev_i32_e32 v131, 31, v130
	v_lshlrev_b64 v[132:133], 6, v[172:173]
	v_lshl_add_u64 v[132:133], s[74:75], 0, v[132:133]
	v_lshlrev_b64 v[176:177], 2, v[130:131]
	v_or_b32_e32 v188, 16, v172
	v_lshl_add_u64 v[130:131], v[132:133], 0, v[176:177]
	v_ashrrev_i32_e32 v189, 31, v188
	global_load_dwordx4 v[134:137], v[130:131], off
	v_lshlrev_b64 v[130:131], 6, v[188:189]
	v_lshl_add_u64 v[130:131], s[74:75], 0, v[130:131]
	v_lshl_add_u64 v[130:131], v[130:131], 0, v[176:177]
	global_load_dwordx4 v[142:145], v[130:131], off
	s_lshl_b32 s29, s92, 8
	s_ashr_i32 s28, s28, 1
	s_or_b32 s29, s29, s21
	s_and_b32 s28, s28, 0xfffff000
	s_cmp_lt_i32 s97, 0
	s_cselect_b32 s28, s28, 0x8000
	v_lshl_add_u32 v194, v138, 3, s29
	s_ashr_i32 s29, s28, 31
	s_lshl_b64 s[28:29], s[28:29], 2
	s_add_u32 s28, s65, s28
	s_mov_b32 s40, 0x358637bd
	v_ashrrev_i32_e32 v195, 31, v194
	s_addc_u32 s29, s24, s29
	v_mov_b64_e32 v[168:169], s[40:41]
	v_lshl_add_u64 v[148:149], v[194:195], 2, s[28:29]
	s_mov_b32 s28, 0x3a800000
	v_or_b32_e32 v186, 32, v172
	v_ashrrev_i32_e32 v187, 31, v186
	v_or_b32_e32 v180, 48, v172
	v_lshlrev_b64 v[130:131], 6, v[186:187]
	v_ashrrev_i32_e32 v181, 31, v180
	v_lshl_add_u64 v[130:131], s[74:75], 0, v[130:131]
	v_lshlrev_b64 v[150:151], 6, v[180:181]
	v_lshl_add_u64 v[146:147], v[130:131], 0, v[176:177]
	global_load_dwordx4 v[130:133], v[148:149], off offset:16
	global_load_dwordx4 v[138:141], v[148:149], off
	v_lshl_add_u64 v[150:151], s[74:75], 0, v[150:151]
	v_lshl_add_u64 v[150:151], v[150:151], 0, v[176:177]
	v_add_u32_e32 v174, 0x80, v172
	v_add_u32_e32 v170, 0x90, v172
	v_ashrrev_i32_e32 v175, 31, v174
	v_ashrrev_i32_e32 v171, 31, v170
	v_lshlrev_b64 v[190:191], 6, v[174:175]
	v_lshlrev_b64 v[196:197], 6, v[170:171]
	v_add_u32_e32 v166, 0xa0, v172
	v_add_u32_e32 v164, 0xb0, v172
	v_ashrrev_i32_e32 v167, 31, v166
	v_ashrrev_i32_e32 v165, 31, v164
	v_lshlrev_b64 v[186:187], 13, v[186:187]
	v_lshlrev_b64 v[180:181], 13, v[180:181]
	v_lshl_add_u64 v[186:187], s[50:51], 0, v[186:187]
	v_lshl_add_u64 v[198:199], s[50:51], 0, v[180:181]
	v_lshlrev_b64 v[188:189], 13, v[188:189]
	v_lshl_add_u64 v[188:189], s[50:51], 0, v[188:189]
	s_waitcnt vmcnt(0)
	v_mov_b32_e32 v152, v135
	v_mov_b32_e32 v153, v136
	v_mov_b32_e32 v135, v137
	v_pk_add_f32 v[134:135], v[152:153], v[134:135]
	v_mov_b32_e32 v136, v143
	v_mov_b32_e32 v137, v144
	v_mov_b32_e32 v143, v145
	v_pk_add_f32 v[136:137], v[136:137], v[142:143]
	v_pk_add_f32 v[134:135], v[134:135], v[134:135] op_sel:[0,1] op_sel_hi:[1,0]
	v_pk_add_f32 v[136:137], v[136:137], v[136:137] op_sel:[0,1] op_sel_hi:[1,0]
	v_mov_b32_e32 v135, v134
	v_mov_b32_e32 v142, v136
	s_nop 0
	v_permlane16_swap_b32_e32 v134, v135
	v_permlane16_swap_b32_e32 v136, v142
	v_add_f32_e32 v135, v134, v135
	v_add_f32_e32 v134, v136, v142
	v_mov_b32_e32 v137, v135
	v_mov_b32_e32 v136, v134
	s_nop 0
	v_permlane32_swap_b32_e32 v135, v137
	v_permlane32_swap_b32_e32 v134, v136
	v_pk_add_f32 v[134:135], v[134:135], v[136:137]
	s_nop 0
	v_pk_fma_f32 v[134:135], v[134:135], s[28:29], v[168:169] op_sel_hi:[1,0,0]
	s_nop 0
	v_mul_f32_e32 v136, 0x4b800000, v135
	v_mul_f32_e32 v137, 0x4b800000, v134
	v_cmp_gt_f32_e32 vcc, s90, v135
	v_cmp_gt_f32_e64 s[44:45], s90, v134
	s_nop 0
	v_cndmask_b32_e32 v135, v135, v136, vcc
	v_cndmask_b32_e64 v134, v134, v137, s[44:45]
	v_rsq_f32_e32 v152, v135
	v_rsq_f32_e32 v153, v134
	global_load_dwordx4 v[134:137], v[148:149], off offset:528
	global_load_dwordx4 v[142:145], v[148:149], off offset:512
	v_mul_f32_e32 v148, 0x45800000, v152
	v_mul_f32_e32 v149, 0x45800000, v153
	v_cndmask_b32_e32 v184, v152, v148, vcc
	v_cndmask_b32_e64 v182, v153, v149, s[44:45]
	global_load_dwordx4 v[146:149], v[146:147], off
	v_pk_fma_f32 v[128:129], v[128:129], v[184:185], v[140:141] op_sel_hi:[1,0,1]
	global_load_dwordx4 v[150:153], v[150:151], off
	v_pk_fma_f32 v[126:127], v[126:127], v[184:185], v[138:139] op_sel_hi:[1,0,1]
	v_pk_fma_f32 v[124:125], v[124:125], v[184:185], v[132:133] op_sel_hi:[1,0,1]
	v_pk_fma_f32 v[122:123], v[122:123], v[184:185], v[130:131] op_sel_hi:[1,0,1]
	v_pk_fma_f32 v[120:121], v[120:121], v[182:183], v[140:141] op_sel_hi:[1,0,1]
	v_pk_fma_f32 v[118:119], v[118:119], v[182:183], v[138:139] op_sel_hi:[1,0,1]
	v_pk_fma_f32 v[116:117], v[116:117], v[182:183], v[132:133] op_sel_hi:[1,0,1]
	v_pk_fma_f32 v[114:115], v[114:115], v[182:183], v[130:131] op_sel_hi:[1,0,1]
	v_max_f32_e32 v126, 0, v126
	v_max_f32_e32 v122, 0, v122
	v_max_f32_e32 v127, 0, v127
	v_max_f32_e32 v123, 0, v123
	v_max_f32_e32 v128, 0, v128
	v_max_f32_e32 v124, 0, v124
	v_max_f32_e32 v129, 0, v129
	v_max_f32_e32 v125, 0, v125
	v_pk_mul_f32 v[126:127], v[126:127], v[126:127]
	v_pk_mul_f32 v[122:123], v[122:123], v[122:123]
	v_pk_mul_f32 v[128:129], v[128:129], v[128:129]
	v_pk_mul_f32 v[124:125], v[124:125], v[124:125]
	v_max_f32_e32 v118, 0, v118
	v_max_f32_e32 v114, 0, v114
	v_max_f32_e32 v119, 0, v119
	v_max_f32_e32 v115, 0, v115
	v_max_f32_e32 v120, 0, v120
	v_max_f32_e32 v116, 0, v116
	v_max_f32_e32 v121, 0, v121
	v_max_f32_e32 v117, 0, v117
	v_pk_mul_f32 v[118:119], v[118:119], v[118:119]
	v_pk_mul_f32 v[114:115], v[114:115], v[114:115]
	v_pk_mul_f32 v[120:121], v[120:121], v[120:121]
	v_pk_mul_f32 v[116:117], v[116:117], v[116:117]
	s_waitcnt vmcnt(3)
; __device__ __forceinline__ u32x4 pack8(f32x4 v0, f32x4 v1) { u32x4 w; w.x = cvt_pk_bf16(v0[0], v0[1]); w.y = cvt_pk_bf16(v0[2], v0[3]); w.z = cvt_pk_bf16(v1[0], v1[1]); w.w = cvt_pk_bf16(v1[2], v1[3]); return w; }
; __device__ __forceinline__ float row_rstd16_q(const float* ssqx, int row, int fq) {
;     const f32x4 s0 = *(const f32x4*)(ssqx + (size_t)row * 16 + 4 * fq); float s = (s0[0] + s0[1]) + (s0[2] + s0[3]);
;     { auto r = __builtin_amdgcn_permlane16_swap(__float_as_uint(s), __float_as_uint(s), false, false); s = __uint_as_float(r[0]) + __uint_as_float(r[1]); }
;     { auto r = __builtin_amdgcn_permlane32_swap(__float_as_uint(s), __float_as_uint(s), false, false); s = __uint_as_float(r[0]) + __uint_as_float(r[1]); }
;     return rsqrtf(s * (1.0f / 1024.0f) + 1e-6f);
; }
;     __device__ __forceinline__ void operator()(const f32x4 (&acc)[2][2][4][2], const Unit& u, int wr, int wc, int fr, int fq) const {
;     ...
;         for (int ai = 0; ai < 2; ++ai) {
; #pragma unroll
;             for (int m = 0; m < 4; ++m) { rsv[ai][m] = row_rstd16_q(ssqx, row0 + ai * HALF + m * 16, fq); if (m & 1) asm volatile("" : "+v"(rsv[ai][m - 1]), "+v"(rsv[ai][m]) :: "memory"); } }
; #pragma unroll
;         for (int ai = 0; ai < 2; ++ai)
; #pragma unroll
;             for (int m = 0; m < 4; ++m) { const int row = row0 + ai * HALF + m * 16; bf16_t* rowp = H + (size_t)row * 4096 + col0; const float rs = rsv[ai][m];
; #pragma unroll
;                 for (int bj = 0; bj < 2; ++bj) { f32x4 v0 = acc[ai][bj][m][0] * rs + sw[bj][0], v1 = acc[ai][bj][m][1] * rs + sw[bj][1];
; #pragma unroll
;                     for (int e = 0; e < 4; ++e) { const float a = fmaxf(v0[e], 0.f), b = fmaxf(v1[e], 0.f); v0[e] = a * a; v1[e] = b * b; }
;                     *(u32x4*)(rowp + bj * HALF) = pack8(v0, v1); }
	v_pk_fma_f32 v[100:101], v[100:101], v[182:183], v[136:137] op_sel_hi:[1,0,1]
	v_pk_fma_f32 v[98:99], v[98:99], v[182:183], v[134:135] op_sel_hi:[1,0,1]
	v_max_f32_e32 v200, 0, v100
	v_max_f32_e32 v202, 0, v101
	s_waitcnt vmcnt(2)
	v_pk_fma_f32 v[102:103], v[102:103], v[182:183], v[142:143] op_sel_hi:[1,0,1]
	v_pk_fma_f32 v[110:111], v[110:111], v[184:185], v[142:143] op_sel_hi:[1,0,1]
	v_pk_fma_f32 v[106:107], v[106:107], v[184:185], v[134:135] op_sel_hi:[1,0,1]
	v_pk_fma_f32 v[108:109], v[108:109], v[184:185], v[136:137] op_sel_hi:[1,0,1]
	s_waitcnt vmcnt(1)
	v_mov_b32_e32 v192, v147
	v_mov_b32_e32 v193, v148
	v_mov_b32_e32 v147, v149
	s_waitcnt vmcnt(0)
	v_mov_b32_e32 v148, v151
	v_mov_b32_e32 v149, v152
	v_mov_b32_e32 v151, v153
	v_pk_add_f32 v[146:147], v[192:193], v[146:147]
	v_pk_add_f32 v[148:149], v[148:149], v[150:151]
	v_pk_add_f32 v[146:147], v[146:147], v[146:147] op_sel:[0,1] op_sel_hi:[1,0]
	v_pk_add_f32 v[148:149], v[148:149], v[148:149] op_sel:[0,1] op_sel_hi:[1,0]
	v_mov_b32_e32 v147, v146
	v_mov_b32_e32 v149, v148
	s_nop 0
	v_permlane16_swap_b32_e32 v146, v147
	v_permlane16_swap_b32_e32 v148, v149
	v_add_f32_e32 v147, v146, v147
	v_add_f32_e32 v146, v148, v149
	v_mov_b32_e32 v149, v147
	v_mov_b32_e32 v148, v146
	s_nop 0
	v_permlane32_swap_b32_e32 v147, v149
	v_permlane32_swap_b32_e32 v146, v148
	v_pk_add_f32 v[146:147], v[146:147], v[148:149]
	v_pk_fma_f32 v[104:105], v[104:105], v[182:183], v[144:145] op_sel_hi:[1,0,1]
	v_pk_fma_f32 v[146:147], v[146:147], s[28:29], v[168:169] op_sel_hi:[1,0,0]
	v_max_f32_e32 v110, 0, v110
	v_mul_f32_e32 v148, 0x4b800000, v147
	v_mul_f32_e32 v149, 0x4b800000, v146
	v_cmp_gt_f32_e32 vcc, s90, v147
	v_cmp_gt_f32_e64 s[44:45], s90, v146
	v_max_f32_e32 v106, 0, v106
	v_cndmask_b32_e32 v147, v147, v148, vcc
	v_cndmask_b32_e64 v146, v146, v149, s[44:45]
	v_rsq_f32_e32 v148, v147
	v_rsq_f32_e32 v149, v146
	v_lshl_add_u64 v[146:147], s[74:75], 0, v[190:191]
	v_lshl_add_u64 v[146:147], v[146:147], 0, v[176:177]
	v_mul_f32_e32 v150, 0x45800000, v148
	v_mul_f32_e32 v151, 0x45800000, v149
	v_cndmask_b32_e32 v192, v148, v150, vcc
	v_cndmask_b32_e64 v178, v149, v151, s[44:45]
	v_lshl_add_u64 v[150:151], s[74:75], 0, v[196:197]
	v_lshl_add_u64 v[150:151], v[150:151], 0, v[176:177]
	global_load_dwordx4 v[146:149], v[146:147], off
	v_lshlrev_b64 v[190:191], 13, v[172:173]
	global_load_dwordx4 v[150:153], v[150:151], off
	v_lshlrev_b64 v[172:173], 1, v[194:195]
	v_lshlrev_b64 v[194:195], 6, v[166:167]
	v_lshlrev_b64 v[196:197], 6, v[164:165]
	v_lshl_add_u64 v[194:195], s[74:75], 0, v[194:195]
	v_lshl_add_u64 v[196:197], s[74:75], 0, v[196:197]
	v_lshl_add_u64 v[194:195], v[194:195], 0, v[176:177]
	v_lshl_add_u64 v[196:197], v[196:197], 0, v[176:177]
	v_lshl_add_u64 v[180:181], v[186:187], 0, v[172:173]
	v_lshl_add_u64 v[176:177], v[198:199], 0, v[172:173]
	v_max_f32_e32 v187, 0, v98
	v_max_f32_e32 v198, 0, v99
	v_max_f32_e32 v186, 0, v102
	v_max_f32_e32 v111, 0, v111
	v_max_f32_e32 v107, 0, v107
	v_pk_fma_f32 v[112:113], v[112:113], v[184:185], v[144:145] op_sel_hi:[1,0,1]
	v_max_f32_e32 v182, 0, v108
	v_max_f32_e32 v184, 0, v109
	v_max_f32_e32 v193, 0, v103
	v_max_f32_e32 v199, 0, v104
	v_max_f32_e32 v201, 0, v105
	v_pk_fma_f32 v[76:77], v[76:77], v[192:193], v[136:137] op_sel_hi:[1,0,1]
	v_pk_fma_f32 v[74:75], v[74:75], v[192:193], v[134:135] op_sel_hi:[1,0,1]
	v_max_f32_e32 v76, 0, v76
	v_max_f32_e32 v74, 0, v74
	v_max_f32_e32 v75, 0, v75
	v_max_f32_e32 v77, 0, v77
	v_pk_fma_f32 v[96:97], v[96:97], v[192:193], v[140:141] op_sel_hi:[1,0,1]
	v_pk_fma_f32 v[94:95], v[94:95], v[192:193], v[138:139] op_sel_hi:[1,0,1]
	v_pk_fma_f32 v[92:93], v[92:93], v[192:193], v[132:133] op_sel_hi:[1,0,1]
	v_pk_fma_f32 v[90:91], v[90:91], v[192:193], v[130:131] op_sel_hi:[1,0,1]
	v_pk_fma_f32 v[80:81], v[80:81], v[192:193], v[144:145] op_sel_hi:[1,0,1]
	v_pk_fma_f32 v[78:79], v[78:79], v[192:193], v[142:143] op_sel_hi:[1,0,1]
	v_lshl_add_u64 v[190:191], s[50:51], 0, v[190:191]
	v_max_f32_e32 v78, 0, v78
	v_max_f32_e32 v79, 0, v79
	v_max_f32_e32 v80, 0, v80
	v_max_f32_e32 v81, 0, v81
	v_lshl_add_u64 v[190:191], v[190:191], 0, v[172:173]
	v_max_f32_e32 v112, 0, v112
	v_max_f32_e32 v113, 0, v113
	v_mul_f32_e32 v192, v79, v79
	v_pk_mul_f32 v[112:113], v[112:113], v[112:113]
	v_lshl_add_u64 v[188:189], v[188:189], 0, v[172:173]
	v_pk_fma_f32 v[88:89], v[88:89], v[178:179], v[140:141] op_sel_hi:[1,0,1]
	v_max_f32_e32 v94, 0, v94
	v_max_f32_e32 v90, 0, v90
	v_max_f32_e32 v95, 0, v95
	v_max_f32_e32 v91, 0, v91
	v_max_f32_e32 v96, 0, v96
	v_max_f32_e32 v92, 0, v92
	v_max_f32_e32 v97, 0, v97
	v_max_f32_e32 v93, 0, v93
	v_pk_fma_f32 v[86:87], v[86:87], v[178:179], v[138:139] op_sel_hi:[1,0,1]
	v_max_f32_e32 v89, 0, v89
	v_pk_mul_f32 v[94:95], v[94:95], v[94:95]
	v_pk_mul_f32 v[90:91], v[90:91], v[90:91]
	v_pk_mul_f32 v[96:97], v[96:97], v[96:97]
	v_pk_mul_f32 v[92:93], v[92:93], v[92:93]
	v_pk_fma_f32 v[68:69], v[68:69], v[178:179], v[136:137] op_sel_hi:[1,0,1]
	v_pk_fma_f32 v[66:67], v[66:67], v[178:179], v[134:135] op_sel_hi:[1,0,1]
	v_pk_fma_f32 v[84:85], v[84:85], v[178:179], v[132:133] op_sel_hi:[1,0,1]
	v_max_f32_e32 v86, 0, v86
	v_max_f32_e32 v87, 0, v87
	v_max_f32_e32 v88, 0, v88
	v_pk_fma_f32 v[72:73], v[72:73], v[178:179], v[144:145] op_sel_hi:[1,0,1]
	v_pk_fma_f32 v[70:71], v[70:71], v[178:179], v[142:143] op_sel_hi:[1,0,1]
	v_max_f32_e32 v66, 0, v66
	v_max_f32_e32 v67, 0, v67
	v_max_f32_e32 v68, 0, v68
	v_pk_fma_f32 v[82:83], v[82:83], v[178:179], v[130:131] op_sel_hi:[1,0,1]
	v_max_f32_e32 v85, 0, v85
	v_mul_f32_e32 v86, v86, v86
	s_waitcnt vmcnt(1)
	v_mov_b32_e32 v98, v147
	v_mov_b32_e32 v99, v148
	v_mov_b32_e32 v147, v149
	s_waitcnt vmcnt(0)
; __device__ __forceinline__ u32x4 pack8(f32x4 v0, f32x4 v1) { u32x4 w; w.x = cvt_pk_bf16(v0[0], v0[1]); w.y = cvt_pk_bf16(v0[2], v0[3]); w.z = cvt_pk_bf16(v1[0], v1[1]); w.w = cvt_pk_bf16(v1[2], v1[3]); return w; }
; __device__ __forceinline__ float row_rstd16_q(const float* ssqx, int row, int fq) {
;     const f32x4 s0 = *(const f32x4*)(ssqx + (size_t)row * 16 + 4 * fq); float s = (s0[0] + s0[1]) + (s0[2] + s0[3]);
;     { auto r = __builtin_amdgcn_permlane16_swap(__float_as_uint(s), __float_as_uint(s), false, false); s = __uint_as_float(r[0]) + __uint_as_float(r[1]); }
;     { auto r = __builtin_amdgcn_permlane32_swap(__float_as_uint(s), __float_as_uint(s), false, false); s = __uint_as_float(r[0]) + __uint_as_float(r[1]); }
;     return rsqrtf(s * (1.0f / 1024.0f) + 1e-6f);
; }
;     __device__ __forceinline__ void operator()(const f32x4 (&acc)[2][2][4][2], const Unit& u, int wr, int wc, int fr, int fq) const {
;     ...
;             for (int m = 0; m < 4; ++m) { const int row = row0 + ai * HALF + m * 16; bf16_t* rowp = H + (size_t)row * 4096 + col0; const float rs = rsv[ai][m];
; #pragma unroll
;                 for (int bj = 0; bj < 2; ++bj) { f32x4 v0 = acc[ai][bj][m][0] * rs + sw[bj][0], v1 = acc[ai][bj][m][1] * rs + sw[bj][1];
; #pragma unroll
;                     for (int e = 0; e < 4; ++e) { const float a = fmaxf(v0[e], 0.f), b = fmaxf(v1[e], 0.f); v0[e] = a * a; v1[e] = b * b; }
;                     *(u32x4*)(rowp + bj * HALF) = pack8(v0, v1); }
	v_mov_b32_e32 v100, v151
	v_mov_b32_e32 v101, v152
	v_mov_b32_e32 v151, v153
	v_pk_add_f32 v[98:99], v[98:99], v[146:147]
	v_pk_add_f32 v[100:101], v[100:101], v[150:151]
	v_pk_add_f32 v[98:99], v[98:99], v[98:99] op_sel:[0,1] op_sel_hi:[1,0]
	v_pk_add_f32 v[100:101], v[100:101], v[100:101] op_sel:[0,1] op_sel_hi:[1,0]
	v_mov_b32_e32 v99, v98
	v_mov_b32_e32 v101, v100
	s_nop 0
	v_permlane16_swap_b32_e32 v98, v99
	v_permlane16_swap_b32_e32 v100, v101
	v_add_f32_e32 v99, v98, v99
	v_add_f32_e32 v98, v100, v101
	v_mov_b32_e32 v101, v99
	v_mov_b32_e32 v100, v98
	s_nop 0
	v_permlane32_swap_b32_e32 v99, v101
	v_permlane32_swap_b32_e32 v98, v100
	v_pk_add_f32 v[98:99], v[98:99], v[100:101]
	v_mul_f32_e32 v149, v187, v187
	v_pk_fma_f32 v[98:99], v[98:99], s[28:29], v[168:169] op_sel_hi:[1,0,0]
	v_mul_f32_e32 v150, v193, v193
	v_mul_f32_e32 v100, 0x4b800000, v99
	v_mul_f32_e32 v101, 0x4b800000, v98
	v_cmp_gt_f32_e32 vcc, s90, v99
	v_cmp_gt_f32_e64 s[44:45], s90, v98
	v_mul_f32_e32 v187, v74, v74
	v_cndmask_b32_e32 v99, v99, v100, vcc
	v_cndmask_b32_e64 v98, v98, v101, s[44:45]
	v_rsq_f32_e32 v99, v99
	v_rsq_f32_e32 v98, v98
	v_mul_f32_e32 v101, v110, v110
	v_mul_f32_e32 v110, v106, v106
	v_mul_f32_e32 v100, 0x45800000, v99
	v_mul_f32_e32 v102, 0x45800000, v98
	v_cndmask_b32_e32 v100, v99, v100, vcc
	v_cndmask_b32_e64 v98, v98, v102, s[44:45]
	global_load_dwordx4 v[102:105], v[194:195], off
	v_mul_f32_e32 v99, v111, v111
	v_mul_f32_e32 v111, v107, v107
	global_load_dwordx4 v[106:109], v[196:197], off
	v_mul_f32_e32 v193, v75, v75
	v_mul_f32_e32 v195, v76, v76
	v_mul_f32_e32 v197, v77, v77
	v_mul_f32_e32 v148, v186, v186
	v_mul_f32_e32 v186, v78, v78
	v_mul_f32_e32 v194, v80, v80
	v_mul_f32_e32 v196, v81, v81
	v_mul_f32_e32 v146, v182, v182
	v_mul_f32_e32 v147, v184, v184
	v_mul_f32_e32 v151, v198, v198
	v_mul_f32_e32 v152, v199, v199
	v_mul_f32_e32 v153, v200, v200
	v_mul_f32_e32 v182, v201, v201
	v_mul_f32_e32 v184, v202, v202
	v_mul_f32_e32 v87, v87, v87
	v_max_f32_e32 v82, 0, v82
	v_max_f32_e32 v83, 0, v83
	v_max_f32_e32 v84, 0, v84
	v_max_f32_e32 v70, 0, v70
	v_max_f32_e32 v69, 0, v69
	v_pk_fma_f32 v[58:59], v[58:59], v[100:101], v[130:131] op_sel_hi:[1,0,1]
	v_pk_mul_f32 v[82:83], v[82:83], v[82:83]
	v_mul_f32_e32 v84, v84, v84
	v_mul_f32_e32 v70, v70, v70
	v_mul_f32_e32 v69, v69, v69
	v_pk_fma_f32 v[62:63], v[62:63], v[100:101], v[138:139] op_sel_hi:[1,0,1]
	v_pk_fma_f32 v[60:61], v[60:61], v[100:101], v[132:133] op_sel_hi:[1,0,1]
	v_max_f32_e32 v58, 0, v58
	v_pk_fma_f32 v[64:65], v[64:65], v[100:101], v[140:141] op_sel_hi:[1,0,1]
	v_max_f32_e32 v59, 0, v59
	v_max_f32_e32 v60, 0, v60
	v_max_f32_e32 v62, 0, v62
	v_max_f32_e32 v61, 0, v61
	v_pk_fma_f32 v[52:53], v[52:53], v[100:101], v[136:137] op_sel_hi:[1,0,1]
	v_pk_fma_f32 v[50:51], v[50:51], v[100:101], v[134:135] op_sel_hi:[1,0,1]
	v_mul_f32_e32 v62, v62, v62
	v_mul_f32_e32 v61, v61, v61
	v_pk_fma_f32 v[56:57], v[56:57], v[100:101], v[144:145] op_sel_hi:[1,0,1]
	v_pk_fma_f32 v[54:55], v[54:55], v[100:101], v[142:143] op_sel_hi:[1,0,1]
	v_max_f32_e32 v50, 0, v50
	v_max_f32_e32 v51, 0, v51
	v_max_f32_e32 v52, 0, v52
	v_max_f32_e32 v54, 0, v54
	v_max_f32_e32 v53, 0, v53
	v_pk_fma_f32 v[42:43], v[42:43], v[98:99], v[130:131] op_sel_hi:[1,0,1]
	v_mul_f32_e32 v54, v54, v54
	v_mul_f32_e32 v53, v53, v53
	v_pk_fma_f32 v[46:47], v[46:47], v[98:99], v[138:139] op_sel_hi:[1,0,1]
	v_pk_fma_f32 v[44:45], v[44:45], v[98:99], v[132:133] op_sel_hi:[1,0,1]
	v_max_f32_e32 v42, 0, v42
	v_pk_fma_f32 v[48:49], v[48:49], v[98:99], v[140:141] op_sel_hi:[1,0,1]
	v_max_f32_e32 v43, 0, v43
	v_max_f32_e32 v44, 0, v44
	v_max_f32_e32 v46, 0, v46
	v_max_f32_e32 v45, 0, v45
	v_pk_fma_f32 v[36:37], v[36:37], v[98:99], v[136:137] op_sel_hi:[1,0,1]
	v_pk_fma_f32 v[34:35], v[34:35], v[98:99], v[134:135] op_sel_hi:[1,0,1]
	v_mul_f32_e32 v46, v46, v46
	v_mul_f32_e32 v45, v45, v45
	v_pk_fma_f32 v[40:41], v[40:41], v[98:99], v[144:145] op_sel_hi:[1,0,1]
	v_pk_fma_f32 v[38:39], v[38:39], v[98:99], v[142:143] op_sel_hi:[1,0,1]
	v_max_f32_e32 v34, 0, v34
	v_max_f32_e32 v35, 0, v35
	v_max_f32_e32 v36, 0, v36
	v_max_f32_e32 v38, 0, v38
	v_max_f32_e32 v37, 0, v37
	v_mul_f32_e32 v38, v38, v38
	v_mul_f32_e32 v37, v37, v37
	s_waitcnt vmcnt(1)
	v_mov_b32_e32 v74, v103
	v_mov_b32_e32 v75, v104
	v_mov_b32_e32 v103, v105
	s_waitcnt vmcnt(0)
; __device__ __forceinline__ u32x4 pack8(f32x4 v0, f32x4 v1) { u32x4 w; w.x = cvt_pk_bf16(v0[0], v0[1]); w.y = cvt_pk_bf16(v0[2], v0[3]); w.z = cvt_pk_bf16(v1[0], v1[1]); w.w = cvt_pk_bf16(v1[2], v1[3]); return w; }
; __device__ __forceinline__ float row_rstd16_q(const float* ssqx, int row, int fq) {
;     const f32x4 s0 = *(const f32x4*)(ssqx + (size_t)row * 16 + 4 * fq); float s = (s0[0] + s0[1]) + (s0[2] + s0[3]);
;     { auto r = __builtin_amdgcn_permlane16_swap(__float_as_uint(s), __float_as_uint(s), false, false); s = __uint_as_float(r[0]) + __uint_as_float(r[1]); }
;     { auto r = __builtin_amdgcn_permlane32_swap(__float_as_uint(s), __float_as_uint(s), false, false); s = __uint_as_float(r[0]) + __uint_as_float(r[1]); }
;     return rsqrtf(s * (1.0f / 1024.0f) + 1e-6f);
; }
;     __device__ __forceinline__ void operator()(const f32x4 (&acc)[2][2][4][2], const Unit& u, int wr, int wc, int fr, int fq) const {
;     ...
;             for (int m = 0; m < 4; ++m) { const int row = row0 + ai * HALF + m * 16; bf16_t* rowp = H + (size_t)row * 4096 + col0; const float rs = rsv[ai][m];
; #pragma unroll
;                 for (int bj = 0; bj < 2; ++bj) { f32x4 v0 = acc[ai][bj][m][0] * rs + sw[bj][0], v1 = acc[ai][bj][m][1] * rs + sw[bj][1];
; #pragma unroll
;                     for (int e = 0; e < 4; ++e) { const float a = fmaxf(v0[e], 0.f), b = fmaxf(v1[e], 0.f); v0[e] = a * a; v1[e] = b * b; }
;                     *(u32x4*)(rowp + bj * HALF) = pack8(v0, v1); }
	v_mov_b32_e32 v76, v107
	v_mov_b32_e32 v77, v108
	v_mov_b32_e32 v107, v109
	v_pk_add_f32 v[74:75], v[74:75], v[102:103]
	v_pk_add_f32 v[76:77], v[76:77], v[106:107]
	v_pk_add_f32 v[74:75], v[74:75], v[74:75] op_sel:[0,1] op_sel_hi:[1,0]
	v_pk_add_f32 v[76:77], v[76:77], v[76:77] op_sel:[0,1] op_sel_hi:[1,0]
	v_mov_b32_e32 v75, v74
	v_mov_b32_e32 v77, v76
	s_nop 0
	v_permlane16_swap_b32_e32 v74, v75
	v_permlane16_swap_b32_e32 v76, v77
	v_add_f32_e32 v75, v74, v75
	v_add_f32_e32 v74, v76, v77
	v_mov_b32_e32 v77, v75
	v_mov_b32_e32 v76, v74
	s_nop 0
	v_permlane32_swap_b32_e32 v75, v77
	v_permlane32_swap_b32_e32 v74, v76
	v_pk_add_f32 v[74:75], v[74:75], v[76:77]
	s_nop 0
	v_pk_fma_f32 v[74:75], v[74:75], s[28:29], v[168:169] op_sel_hi:[1,0,0]
	s_nop 0
	v_mul_f32_e32 v76, 0x4b800000, v75
	v_mul_f32_e32 v77, 0x4b800000, v74
	v_cmp_gt_f32_e32 vcc, s90, v75
	v_cmp_gt_f32_e64 s[44:45], s90, v74
	s_nop 0
	v_cndmask_b32_e32 v75, v75, v76, vcc
	v_cndmask_b32_e64 v74, v74, v77, s[44:45]
	v_rsq_f32_e32 v75, v75
	v_rsq_f32_e32 v74, v74
	v_mul_f32_e32 v77, v88, v88
	v_mul_f32_e32 v76, 0x45800000, v75
	v_mul_f32_e32 v78, 0x45800000, v74
	v_cndmask_b32_e32 v76, v75, v76, vcc
	v_cndmask_b32_e64 v74, v74, v78, s[44:45]
	v_cvt_pk_bf16_f32 v78, v126, v127
	v_cvt_pk_bf16_f32 v79, v128, v129
	v_cvt_pk_bf16_f32 v80, v122, v123
	v_cvt_pk_bf16_f32 v81, v124, v125
	global_store_dwordx4 v[190:191], v[78:81], off
	v_mul_f32_e32 v75, v89, v89
	v_pk_fma_f32 v[26:27], v[26:27], v[76:77], v[130:131] op_sel_hi:[1,0,1]
	v_cvt_pk_bf16_f32 v78, v101, v99
	v_cvt_pk_bf16_f32 v79, v112, v113
	v_cvt_pk_bf16_f32 v80, v110, v111
	v_cvt_pk_bf16_f32 v81, v146, v147
	global_store_dwordx4 v[190:191], v[78:81], off offset:256
	v_pk_fma_f32 v[30:31], v[30:31], v[76:77], v[138:139] op_sel_hi:[1,0,1]
	v_pk_fma_f32 v[28:29], v[28:29], v[76:77], v[132:133] op_sel_hi:[1,0,1]
	v_cvt_pk_bf16_f32 v78, v118, v119
	v_cvt_pk_bf16_f32 v79, v120, v121
	v_cvt_pk_bf16_f32 v80, v114, v115
	v_cvt_pk_bf16_f32 v81, v116, v117
	global_store_dwordx4 v[188:189], v[78:81], off
	v_max_f32_e32 v26, 0, v26
	v_pk_fma_f32 v[32:33], v[32:33], v[76:77], v[140:141] op_sel_hi:[1,0,1]
	v_cvt_pk_bf16_f32 v78, v148, v150
	v_cvt_pk_bf16_f32 v79, v152, v182
	v_cvt_pk_bf16_f32 v80, v149, v151
	v_cvt_pk_bf16_f32 v81, v153, v184
	global_store_dwordx4 v[188:189], v[78:81], off offset:256
	v_max_f32_e32 v27, 0, v27
	v_max_f32_e32 v28, 0, v28
	v_cvt_pk_bf16_f32 v78, v94, v95
	v_cvt_pk_bf16_f32 v79, v96, v97
	v_cvt_pk_bf16_f32 v80, v90, v91
	v_cvt_pk_bf16_f32 v81, v92, v93
	global_store_dwordx4 v[180:181], v[78:81], off
	v_max_f32_e32 v30, 0, v30
	v_max_f32_e32 v29, 0, v29
	v_cvt_pk_bf16_f32 v78, v186, v192
	v_cvt_pk_bf16_f32 v79, v194, v196
	v_cvt_pk_bf16_f32 v80, v187, v193
	v_cvt_pk_bf16_f32 v81, v195, v197
	global_store_dwordx4 v[180:181], v[78:81], off offset:256
	v_pk_fma_f32 v[20:21], v[20:21], v[76:77], v[136:137] op_sel_hi:[1,0,1]
	v_pk_fma_f32 v[18:19], v[18:19], v[76:77], v[134:135] op_sel_hi:[1,0,1]
	v_cvt_pk_bf16_f32 v78, v86, v87
	v_cvt_pk_bf16_f32 v79, v77, v75
	v_mul_f32_e32 v75, v66, v66
	v_max_f32_e32 v66, 0, v71
	v_mul_f32_e32 v71, v67, v67
	v_max_f32_e32 v67, 0, v72
	v_mul_f32_e32 v72, v68, v68
	v_max_f32_e32 v68, 0, v73
	v_mul_f32_e32 v81, v85, v85
	v_pk_mul_f32 v[66:67], v[66:67], v[66:67]
	v_mul_f32_e32 v68, v68, v68
	v_cvt_pk_bf16_f32 v80, v82, v83
	v_cvt_pk_bf16_f32 v81, v84, v81
	global_store_dwordx4 v[176:177], v[78:81], off
	v_cvt_pk_bf16_f32 v66, v70, v66
	v_cvt_pk_bf16_f32 v67, v67, v68
	v_cvt_pk_bf16_f32 v68, v75, v71
	v_cvt_pk_bf16_f32 v69, v72, v69
	global_store_dwordx4 v[176:177], v[66:69], off offset:256
	v_mul_f32_e32 v30, v30, v30
	v_mul_f32_e32 v29, v29, v29
	v_lshlrev_b64 v[66:67], 13, v[174:175]
	v_mul_f32_e32 v68, v58, v58
	v_max_f32_e32 v58, 0, v63
	v_lshl_add_u64 v[66:67], s[50:51], 0, v[66:67]
	v_mul_f32_e32 v58, v58, v58
	v_mul_f32_e32 v63, v59, v59
	v_max_f32_e32 v59, 0, v64
	v_mul_f32_e32 v64, v60, v60
	v_max_f32_e32 v60, 0, v65
	v_lshl_add_u64 v[66:67], v[66:67], 0, v[172:173]
	v_mul_f32_e32 v59, v59, v59
	v_mul_f32_e32 v60, v60, v60
	v_cvt_pk_bf16_f32 v58, v62, v58
	v_cvt_pk_bf16_f32 v59, v59, v60
	v_cvt_pk_bf16_f32 v60, v68, v63
	v_cvt_pk_bf16_f32 v61, v64, v61
	global_store_dwordx4 v[66:67], v[58:61], off
	v_pk_fma_f32 v[24:25], v[24:25], v[76:77], v[144:145] op_sel_hi:[1,0,1]
	v_pk_fma_f32 v[22:23], v[22:23], v[76:77], v[142:143] op_sel_hi:[1,0,1]
	v_mul_f32_e32 v58, v50, v50
	v_max_f32_e32 v50, 0, v55
	v_mul_f32_e32 v55, v51, v51
	v_max_f32_e32 v51, 0, v56
	v_mul_f32_e32 v56, v52, v52
	v_max_f32_e32 v52, 0, v57
	v_pk_mul_f32 v[50:51], v[50:51], v[50:51]
	v_mul_f32_e32 v52, v52, v52
	v_cvt_pk_bf16_f32 v50, v54, v50
	v_cvt_pk_bf16_f32 v51, v51, v52
; __device__ __forceinline__ u32x4 pack8(f32x4 v0, f32x4 v1) { u32x4 w; w.x = cvt_pk_bf16(v0[0], v0[1]); w.y = cvt_pk_bf16(v0[2], v0[3]); w.z = cvt_pk_bf16(v1[0], v1[1]); w.w = cvt_pk_bf16(v1[2], v1[3]); return w; }
;     __device__ __forceinline__ void done(const Unit&) const {
;         __builtin_amdgcn_fence(__ATOMIC_RELEASE, "agent"); asm volatile("s_waitcnt vmcnt(0)" ::: "memory");
;         int ln_; asm volatile("v_mbcnt_lo_u32_b32 %0, -1, 0\n\tv_mbcnt_hi_u32_b32 %0, -1, %0" : "=&v"(ln_));
;         if (ln_ == 0) __hip_atomic_fetch_add(cnt, 1u, __ATOMIC_RELAXED, __HIP_MEMORY_SCOPE_AGENT);
;     __device__ __forceinline__ void operator()(const f32x4 (&acc)[2][2][4][2], const Unit& u, int wr, int wc, int fr, int fq) const {
;     ...
;             for (int m = 0; m < 4; ++m) { const int row = row0 + ai * HALF + m * 16; bf16_t* rowp = H + (size_t)row * 4096 + col0; const float rs = rsv[ai][m];
; #pragma unroll
;                 for (int bj = 0; bj < 2; ++bj) { f32x4 v0 = acc[ai][bj][m][0] * rs + sw[bj][0], v1 = acc[ai][bj][m][1] * rs + sw[bj][1];
; #pragma unroll
;                     for (int e = 0; e < 4; ++e) { const float a = fmaxf(v0[e], 0.f), b = fmaxf(v1[e], 0.f); v0[e] = a * a; v1[e] = b * b; }
;                     *(u32x4*)(rowp + bj * HALF) = pack8(v0, v1); }
	v_cvt_pk_bf16_f32 v52, v58, v55
	v_cvt_pk_bf16_f32 v53, v56, v53
	global_store_dwordx4 v[66:67], v[50:53], off offset:256
	v_max_f32_e32 v18, 0, v18
	v_max_f32_e32 v19, 0, v19
	v_lshlrev_b64 v[50:51], 13, v[170:171]
	v_mul_f32_e32 v52, v42, v42
	v_max_f32_e32 v42, 0, v47
	v_lshl_add_u64 v[50:51], s[50:51], 0, v[50:51]
	v_mul_f32_e32 v42, v42, v42
	v_mul_f32_e32 v47, v43, v43
	v_max_f32_e32 v43, 0, v48
	v_mul_f32_e32 v48, v44, v44
	v_max_f32_e32 v44, 0, v49
	v_lshl_add_u64 v[50:51], v[50:51], 0, v[172:173]
	v_mul_f32_e32 v43, v43, v43
	v_mul_f32_e32 v44, v44, v44
	v_cvt_pk_bf16_f32 v42, v46, v42
	v_cvt_pk_bf16_f32 v43, v43, v44
	v_cvt_pk_bf16_f32 v44, v52, v47
	v_cvt_pk_bf16_f32 v45, v48, v45
	global_store_dwordx4 v[50:51], v[42:45], off
	v_max_f32_e32 v20, 0, v20
	v_max_f32_e32 v22, 0, v22
	v_mul_f32_e32 v42, v34, v34
	v_max_f32_e32 v34, 0, v39
	v_mul_f32_e32 v39, v35, v35
	v_max_f32_e32 v35, 0, v40
	v_mul_f32_e32 v40, v36, v36
	v_max_f32_e32 v36, 0, v41
	v_pk_mul_f32 v[34:35], v[34:35], v[34:35]
	v_mul_f32_e32 v36, v36, v36
	v_cvt_pk_bf16_f32 v34, v38, v34
	v_cvt_pk_bf16_f32 v35, v35, v36
	v_cvt_pk_bf16_f32 v36, v42, v39
	v_cvt_pk_bf16_f32 v37, v40, v37
	global_store_dwordx4 v[50:51], v[34:37], off offset:256
	v_max_f32_e32 v21, 0, v21
	v_pk_fma_f32 v[10:11], v[10:11], v[74:75], v[130:131] op_sel_hi:[1,0,1]
	v_lshlrev_b64 v[34:35], 13, v[166:167]
	v_mul_f32_e32 v36, v26, v26
	v_max_f32_e32 v26, 0, v31
	v_lshl_add_u64 v[34:35], s[50:51], 0, v[34:35]
	v_mul_f32_e32 v26, v26, v26
	v_mul_f32_e32 v31, v27, v27
	v_max_f32_e32 v27, 0, v32
	v_mul_f32_e32 v32, v28, v28
	v_max_f32_e32 v28, 0, v33
	v_lshl_add_u64 v[34:35], v[34:35], 0, v[172:173]
	v_mul_f32_e32 v27, v27, v27
	v_mul_f32_e32 v28, v28, v28
	v_cvt_pk_bf16_f32 v26, v30, v26
	v_cvt_pk_bf16_f32 v27, v27, v28
	v_cvt_pk_bf16_f32 v28, v36, v31
	v_cvt_pk_bf16_f32 v29, v32, v29
	global_store_dwordx4 v[34:35], v[26:29], off
	v_mul_f32_e32 v22, v22, v22
	v_mul_f32_e32 v21, v21, v21
	v_mul_f32_e32 v26, v18, v18
	v_max_f32_e32 v18, 0, v23
	v_mul_f32_e32 v23, v19, v19
	v_max_f32_e32 v19, 0, v24
	v_mul_f32_e32 v24, v20, v20
	v_max_f32_e32 v20, 0, v25
	v_pk_mul_f32 v[18:19], v[18:19], v[18:19]
	v_mul_f32_e32 v20, v20, v20
	v_cvt_pk_bf16_f32 v18, v22, v18
	v_cvt_pk_bf16_f32 v19, v19, v20
	v_cvt_pk_bf16_f32 v20, v26, v23
	v_pk_fma_f32 v[14:15], v[14:15], v[74:75], v[138:139] op_sel_hi:[1,0,1]
	v_pk_fma_f32 v[12:13], v[12:13], v[74:75], v[132:133] op_sel_hi:[1,0,1]
	v_max_f32_e32 v10, 0, v10
	v_cvt_pk_bf16_f32 v21, v24, v21
	global_store_dwordx4 v[34:35], v[18:21], off offset:256
	v_pk_fma_f32 v[16:17], v[16:17], v[74:75], v[140:141] op_sel_hi:[1,0,1]
	v_max_f32_e32 v11, 0, v11
	v_lshlrev_b64 v[18:19], 13, v[164:165]
	v_mul_f32_e32 v20, v10, v10
	v_max_f32_e32 v10, 0, v15
	v_max_f32_e32 v12, 0, v12
	v_lshl_add_u64 v[18:19], s[50:51], 0, v[18:19]
	v_max_f32_e32 v14, 0, v14
	v_mul_f32_e32 v10, v10, v10
	v_mul_f32_e32 v15, v11, v11
	v_max_f32_e32 v11, 0, v16
	v_mul_f32_e32 v16, v12, v12
	v_max_f32_e32 v12, 0, v17
	v_max_f32_e32 v13, 0, v13
	v_pk_fma_f32 v[4:5], v[4:5], v[74:75], v[136:137] op_sel_hi:[1,0,1]
	v_pk_fma_f32 v[2:3], v[2:3], v[74:75], v[134:135] op_sel_hi:[1,0,1]
	v_lshl_add_u64 v[18:19], v[18:19], 0, v[172:173]
	v_mul_f32_e32 v14, v14, v14
	v_mul_f32_e32 v11, v11, v11
	v_pk_mul_f32 v[12:13], v[12:13], v[12:13]
	v_cvt_pk_bf16_f32 v10, v14, v10
	v_pk_fma_f32 v[8:9], v[8:9], v[74:75], v[144:145] op_sel_hi:[1,0,1]
	v_pk_fma_f32 v[6:7], v[6:7], v[74:75], v[142:143] op_sel_hi:[1,0,1]
	v_max_f32_e32 v2, 0, v2
	v_max_f32_e32 v3, 0, v3
	v_max_f32_e32 v4, 0, v4
	v_cvt_pk_bf16_f32 v11, v11, v12
	v_cvt_pk_bf16_f32 v12, v20, v15
	v_cvt_pk_bf16_f32 v13, v16, v13
	global_store_dwordx4 v[18:19], v[10:13], off
	v_max_f32_e32 v5, 0, v5
	v_max_f32_e32 v6, 0, v6
	v_mul_f32_e32 v10, v2, v2
	v_max_f32_e32 v2, 0, v7
	v_mul_f32_e32 v7, v3, v3
	v_max_f32_e32 v3, 0, v8
	v_mul_f32_e32 v8, v4, v4
	v_max_f32_e32 v4, 0, v9
	v_pk_mul_f32 v[2:3], v[2:3], v[2:3]
	v_pk_mul_f32 v[4:5], v[4:5], v[4:5]
	v_mul_f32_e32 v6, v6, v6
	v_cvt_pk_bf16_f32 v2, v6, v2
	v_cvt_pk_bf16_f32 v3, v3, v4
	v_cvt_pk_bf16_f32 v4, v10, v7
	v_cvt_pk_bf16_f32 v5, v8, v5
	global_store_dwordx4 v[18:19], v[2:5], off offset:256
	buffer_wbl2 sc1
	s_waitcnt vmcnt(0)
	s_waitcnt vmcnt(0)
	v_mbcnt_lo_u32_b32 v2, -1, 0
	v_mbcnt_hi_u32_b32 v2, -1, v2
	s_nop 0
	v_cmp_eq_u32_e32 vcc, 0, v2
	s_and_saveexec_b64 s[44:45], vcc
	s_movk_i32 s78, 0x600
	s_cbranch_execz .LBB0_100
	s_mov_b64 s[82:83], exec
	v_mbcnt_lo_u32_b32 v2, s82, 0
	v_mbcnt_hi_u32_b32 v2, s83, v2
	v_cmp_eq_u32_e32 vcc, 0, v2
	s_and_b64 s[28:29], exec, vcc
	s_mov_b64 exec, s[28:29]
	s_cbranch_execz .LBB0_100
	s_bcnt1_i32_b64 s28, s[82:83]
	v_mov_b32_e32 v2, s28
	global_atomic_add v1, v2, s[46:47]

;     __device__ __forceinline__ void operator()(const f32x4 (&acc)[2][2][4][2], const Unit& u, int wr, int wc, int fr, int fq) const {
;         const int row0 = row_base + u.pm * BM + wr * 64 + fr, col0 = u.pn * BM + wc * 32 + 8 * fq;
;         const int mi = (row_base + u.pm * BM >= T_LAT) ? 8 : ((row_base + u.pm * BM) >> 13);
;         f32x4 sw[2][2];
; #pragma unroll
;         for (int bj = 0; bj < 2; ++bj) { sw[bj][0] = *(const f32x4*)(shw + mi * 4096 + col0 + bj * HALF); sw[bj][1] = *(const f32x4*)(shw + mi * 4096 + col0 + bj * HALF + 4); }
;         float rsv[2][4];
; #pragma unroll
;         for (int ai = 0; ai < 2; ++ai) {
; #pragma unroll
;             for (int m = 0; m < 4; ++m) { rsv[ai][m] = row_rstd16_q(ssqx, row0 + ai * HALF + m * 16, fq); if (m & 1) asm volatile("" : "+v"(rsv[ai][m - 1]), "+v"(rsv[ai][m]) :: "memory"); } }
.LBB0_120:
	v_mbcnt_lo_u32_b32 v130, -1, 0
	v_mbcnt_hi_u32_b32 v130, -1, v130
	s_mov_b32 s28, 0x358637bd
	v_ashrrev_i32_e32 v138, 4, v130
	v_and_or_b32 v130, v130, 15, s20
	v_lshl_add_u32 v172, s97, 8, v130
	v_lshlrev_b32_e32 v130, 2, v138
	v_ashrrev_i32_e32 v173, 31, v172
	v_ashrrev_i32_e32 v131, 31, v130
	v_lshlrev_b64 v[132:133], 6, v[172:173]
	v_lshl_add_u64 v[132:133], s[74:75], 0, v[132:133]
	v_lshlrev_b64 v[176:177], 2, v[130:131]
	v_or_b32_e32 v188, 16, v172
	v_lshl_add_u64 v[130:131], v[132:133], 0, v[176:177]
	v_ashrrev_i32_e32 v189, 31, v188
	global_load_dwordx4 v[134:137], v[130:131], off
	v_lshlrev_b64 v[130:131], 6, v[188:189]
	v_lshl_add_u64 v[130:131], s[74:75], 0, v[130:131]
	v_lshl_add_u64 v[130:131], v[130:131], 0, v[176:177]
	global_load_dwordx4 v[142:145], v[130:131], off
	v_mov_b64_e32 v[168:169], s[28:29]
	s_lshl_b32 s28, s92, 8
	s_lshl_b32 s29, s97, 7
	s_or_b32 s28, s28, s21
	s_and_b32 s29, s29, 0xfffff000
	s_cmpk_lt_i32 s97, 0x100
	v_lshl_add_u32 v194, v138, 3, s28
	s_cselect_b32 s28, s29, 0x8000
	s_ashr_i32 s29, s28, 31
	s_lshl_b64 s[28:29], s[28:29], 2
	s_add_u32 s28, s65, s28
	v_ashrrev_i32_e32 v195, 31, v194
	s_addc_u32 s29, s24, s29
	v_lshl_add_u64 v[148:149], v[194:195], 2, s[28:29]
	s_mov_b32 s28, 0x3a800000
	v_or_b32_e32 v186, 32, v172
	v_ashrrev_i32_e32 v187, 31, v186
	v_or_b32_e32 v180, 48, v172
	v_lshlrev_b64 v[130:131], 6, v[186:187]
	v_ashrrev_i32_e32 v181, 31, v180
	v_lshl_add_u64 v[130:131], s[74:75], 0, v[130:131]
	v_lshlrev_b64 v[150:151], 6, v[180:181]
	v_lshl_add_u64 v[146:147], v[130:131], 0, v[176:177]
	global_load_dwordx4 v[130:133], v[148:149], off offset:16
	global_load_dwordx4 v[138:141], v[148:149], off
	v_lshl_add_u64 v[150:151], s[74:75], 0, v[150:151]
	v_lshl_add_u64 v[150:151], v[150:151], 0, v[176:177]
	v_add_u32_e32 v174, 0x80, v172
	v_add_u32_e32 v170, 0x90, v172
	v_ashrrev_i32_e32 v175, 31, v174
	v_ashrrev_i32_e32 v171, 31, v170
	v_lshlrev_b64 v[190:191], 6, v[174:175]
	v_lshlrev_b64 v[196:197], 6, v[170:171]
	v_add_u32_e32 v166, 0xa0, v172
	v_add_u32_e32 v164, 0xb0, v172
	v_ashrrev_i32_e32 v167, 31, v166
	v_ashrrev_i32_e32 v165, 31, v164
	v_lshlrev_b64 v[172:173], 13, v[172:173]
	v_lshl_add_u64 v[198:199], s[50:51], 0, v[172:173]
	v_lshlrev_b64 v[172:173], 1, v[194:195]
	v_lshlrev_b64 v[186:187], 13, v[186:187]
	v_lshlrev_b64 v[180:181], 13, v[180:181]
	v_lshl_add_u64 v[186:187], s[50:51], 0, v[186:187]
	v_lshlrev_b64 v[188:189], 13, v[188:189]
	v_lshl_add_u64 v[188:189], s[50:51], 0, v[188:189]
	v_lshl_add_u64 v[188:189], v[188:189], 0, v[172:173]
	s_movk_i32 s78, 0x600
	s_waitcnt vmcnt(0)
	v_mov_b32_e32 v152, v135
	v_mov_b32_e32 v153, v136
	v_mov_b32_e32 v135, v137
	v_pk_add_f32 v[134:135], v[152:153], v[134:135]
	v_mov_b32_e32 v136, v143
	v_mov_b32_e32 v137, v144
	v_mov_b32_e32 v143, v145
	v_pk_add_f32 v[136:137], v[136:137], v[142:143]
	v_pk_add_f32 v[134:135], v[134:135], v[134:135] op_sel:[0,1] op_sel_hi:[1,0]
	v_pk_add_f32 v[136:137], v[136:137], v[136:137] op_sel:[0,1] op_sel_hi:[1,0]
	v_mov_b32_e32 v135, v134
	v_mov_b32_e32 v142, v136
	s_nop 0
	v_permlane16_swap_b32_e32 v134, v135
	v_permlane16_swap_b32_e32 v136, v142
	v_add_f32_e32 v135, v134, v135
	v_add_f32_e32 v134, v136, v142
	v_mov_b32_e32 v137, v135
	v_mov_b32_e32 v136, v134
	s_nop 0
	v_permlane32_swap_b32_e32 v135, v137
	v_permlane32_swap_b32_e32 v134, v136
	v_pk_add_f32 v[134:135], v[134:135], v[136:137]
	s_nop 0
	v_pk_fma_f32 v[134:135], v[134:135], s[28:29], v[168:169] op_sel_hi:[1,0,0]
	s_nop 0
	v_mul_f32_e32 v136, 0x4b800000, v135
	v_mul_f32_e32 v137, 0x4b800000, v134
	v_cmp_gt_f32_e32 vcc, s90, v135
	v_cmp_gt_f32_e64 s[44:45], s90, v134
	s_nop 0
	v_cndmask_b32_e32 v135, v135, v136, vcc
	v_cndmask_b32_e64 v134, v134, v137, s[44:45]
	v_rsq_f32_e32 v152, v135
	v_rsq_f32_e32 v153, v134
	global_load_dwordx4 v[134:137], v[148:149], off offset:528
	global_load_dwordx4 v[142:145], v[148:149], off offset:512
	v_mul_f32_e32 v148, 0x45800000, v152
	v_mul_f32_e32 v149, 0x45800000, v153
	v_cndmask_b32_e32 v184, v152, v148, vcc
	v_cndmask_b32_e64 v182, v153, v149, s[44:45]
	global_load_dwordx4 v[146:149], v[146:147], off
	v_pk_fma_f32 v[128:129], v[128:129], v[184:185], v[140:141] op_sel_hi:[1,0,1]
	global_load_dwordx4 v[150:153], v[150:151], off
	v_pk_fma_f32 v[126:127], v[126:127], v[184:185], v[138:139] op_sel_hi:[1,0,1]
	v_pk_fma_f32 v[124:125], v[124:125], v[184:185], v[132:133] op_sel_hi:[1,0,1]
	v_pk_fma_f32 v[122:123], v[122:123], v[184:185], v[130:131] op_sel_hi:[1,0,1]
	v_pk_fma_f32 v[120:121], v[120:121], v[182:183], v[140:141] op_sel_hi:[1,0,1]
	v_pk_fma_f32 v[118:119], v[118:119], v[182:183], v[138:139] op_sel_hi:[1,0,1]
	v_pk_fma_f32 v[116:117], v[116:117], v[182:183], v[132:133] op_sel_hi:[1,0,1]
	v_pk_fma_f32 v[114:115], v[114:115], v[182:183], v[130:131] op_sel_hi:[1,0,1]
	v_max_f32_e32 v126, 0, v126
	v_max_f32_e32 v122, 0, v122
	v_max_f32_e32 v127, 0, v127
	v_max_f32_e32 v123, 0, v123
	v_max_f32_e32 v128, 0, v128
	v_max_f32_e32 v124, 0, v124
	v_max_f32_e32 v129, 0, v129
	v_max_f32_e32 v125, 0, v125
	v_pk_mul_f32 v[126:127], v[126:127], v[126:127]
	v_pk_mul_f32 v[122:123], v[122:123], v[122:123]
	v_pk_mul_f32 v[128:129], v[128:129], v[128:129]
	v_pk_mul_f32 v[124:125], v[124:125], v[124:125]
	v_max_f32_e32 v118, 0, v118
	v_max_f32_e32 v114, 0, v114
	v_max_f32_e32 v119, 0, v119
	v_max_f32_e32 v115, 0, v115
	v_max_f32_e32 v120, 0, v120
	v_max_f32_e32 v116, 0, v116
	v_max_f32_e32 v121, 0, v121
	v_max_f32_e32 v117, 0, v117
	v_pk_mul_f32 v[118:119], v[118:119], v[118:119]
	v_pk_mul_f32 v[114:115], v[114:115], v[114:115]
	v_pk_mul_f32 v[120:121], v[120:121], v[120:121]
	v_pk_mul_f32 v[116:117], v[116:117], v[116:117]
	s_waitcnt vmcnt(3)
;     __device__ __forceinline__ void operator()(const f32x4 (&acc)[2][2][4][2], const Unit& u, int wr, int wc, int fr, int fq) const {
;     ...
;             for (int m = 0; m < 4; ++m) { rsv[ai][m] = row_rstd16_q(ssqx, row0 + ai * HALF + m * 16, fq); if (m & 1) asm volatile("" : "+v"(rsv[ai][m - 1]), "+v"(rsv[ai][m]) :: "memory"); } }
; #pragma unroll
;         for (int ai = 0; ai < 2; ++ai)
; #pragma unroll
;             for (int m = 0; m < 4; ++m) { const int row = row0 + ai * HALF + m * 16; bf16_t* rowp = H + (size_t)row * 4096 + col0; const float rs = rsv[ai][m];
; #pragma unroll
;                 for (int bj = 0; bj < 2; ++bj) { f32x4 v0 = acc[ai][bj][m][0] * rs + sw[bj][0], v1 = acc[ai][bj][m][1] * rs + sw[bj][1];
; #pragma unroll
;                     for (int e = 0; e < 4; ++e) { const float a = fmaxf(v0[e], 0.f), b = fmaxf(v1[e], 0.f); v0[e] = a * a; v1[e] = b * b; }
	v_pk_fma_f32 v[100:101], v[100:101], v[182:183], v[136:137] op_sel_hi:[1,0,1]
	v_pk_fma_f32 v[98:99], v[98:99], v[182:183], v[134:135] op_sel_hi:[1,0,1]
	v_max_f32_e32 v200, 0, v100
	v_max_f32_e32 v202, 0, v101
	s_waitcnt vmcnt(2)
	v_pk_fma_f32 v[102:103], v[102:103], v[182:183], v[142:143] op_sel_hi:[1,0,1]
	v_pk_fma_f32 v[106:107], v[106:107], v[184:185], v[134:135] op_sel_hi:[1,0,1]
	v_pk_fma_f32 v[108:109], v[108:109], v[184:185], v[136:137] op_sel_hi:[1,0,1]
	v_pk_fma_f32 v[104:105], v[104:105], v[182:183], v[144:145] op_sel_hi:[1,0,1]
	s_waitcnt vmcnt(1)
	v_mov_b32_e32 v192, v147
	v_mov_b32_e32 v193, v148
	v_mov_b32_e32 v147, v149
	s_waitcnt vmcnt(0)
	v_mov_b32_e32 v148, v151
	v_mov_b32_e32 v149, v152
	v_mov_b32_e32 v151, v153
	v_pk_add_f32 v[146:147], v[192:193], v[146:147]
	v_pk_add_f32 v[148:149], v[148:149], v[150:151]
	v_pk_add_f32 v[146:147], v[146:147], v[146:147] op_sel:[0,1] op_sel_hi:[1,0]
	v_pk_add_f32 v[148:149], v[148:149], v[148:149] op_sel:[0,1] op_sel_hi:[1,0]
	v_mov_b32_e32 v147, v146
	v_mov_b32_e32 v149, v148
	s_nop 0
	v_permlane16_swap_b32_e32 v146, v147
	v_permlane16_swap_b32_e32 v148, v149
	v_add_f32_e32 v147, v146, v147
	v_add_f32_e32 v146, v148, v149
	v_mov_b32_e32 v149, v147
	v_mov_b32_e32 v148, v146
	s_nop 0
	v_permlane32_swap_b32_e32 v147, v149
	v_permlane32_swap_b32_e32 v146, v148
	v_pk_add_f32 v[146:147], v[146:147], v[148:149]
	v_max_f32_e32 v106, 0, v106
	v_pk_fma_f32 v[146:147], v[146:147], s[28:29], v[168:169] op_sel_hi:[1,0,0]
	v_max_f32_e32 v107, 0, v107
	v_mul_f32_e32 v148, 0x4b800000, v147
	v_mul_f32_e32 v149, 0x4b800000, v146
	v_cmp_gt_f32_e32 vcc, s90, v147
	v_cmp_gt_f32_e64 s[44:45], s90, v146
	v_pk_fma_f32 v[112:113], v[112:113], v[184:185], v[144:145] op_sel_hi:[1,0,1]
	v_cndmask_b32_e32 v147, v147, v148, vcc
	v_cndmask_b32_e64 v146, v146, v149, s[44:45]
	v_rsq_f32_e32 v148, v147
	v_rsq_f32_e32 v149, v146
	v_lshl_add_u64 v[146:147], s[74:75], 0, v[190:191]
	v_lshl_add_u64 v[146:147], v[146:147], 0, v[176:177]
	v_mul_f32_e32 v150, 0x45800000, v148
	v_mul_f32_e32 v151, 0x45800000, v149
	v_cndmask_b32_e32 v192, v148, v150, vcc
	v_cndmask_b32_e64 v178, v149, v151, s[44:45]
	v_lshl_add_u64 v[150:151], s[74:75], 0, v[196:197]
	v_lshl_add_u64 v[150:151], v[150:151], 0, v[176:177]
	global_load_dwordx4 v[146:149], v[146:147], off
	v_lshlrev_b64 v[190:191], 6, v[166:167]
	global_load_dwordx4 v[150:153], v[150:151], off
	v_lshlrev_b64 v[196:197], 6, v[164:165]
	v_lshl_add_u64 v[190:191], s[74:75], 0, v[190:191]
	v_lshl_add_u64 v[194:195], s[74:75], 0, v[196:197]
	v_lshl_add_u64 v[196:197], v[198:199], 0, v[172:173]
	v_lshl_add_u64 v[198:199], s[50:51], 0, v[180:181]
	v_lshl_add_u64 v[190:191], v[190:191], 0, v[176:177]
	v_lshl_add_u64 v[194:195], v[194:195], 0, v[176:177]
	v_lshl_add_u64 v[180:181], v[186:187], 0, v[172:173]
	v_lshl_add_u64 v[176:177], v[198:199], 0, v[172:173]
	v_max_f32_e32 v187, 0, v98
	v_max_f32_e32 v198, 0, v99
	v_max_f32_e32 v186, 0, v102
	v_pk_fma_f32 v[110:111], v[110:111], v[184:185], v[142:143] op_sel_hi:[1,0,1]
	v_max_f32_e32 v182, 0, v108
	v_max_f32_e32 v184, 0, v109
	v_max_f32_e32 v193, 0, v103
	v_max_f32_e32 v199, 0, v104
	v_max_f32_e32 v201, 0, v105
	v_pk_fma_f32 v[76:77], v[76:77], v[192:193], v[136:137] op_sel_hi:[1,0,1]
	v_pk_fma_f32 v[74:75], v[74:75], v[192:193], v[134:135] op_sel_hi:[1,0,1]
	v_max_f32_e32 v76, 0, v76
	v_max_f32_e32 v74, 0, v74
	v_max_f32_e32 v75, 0, v75
	v_max_f32_e32 v77, 0, v77
	v_pk_fma_f32 v[96:97], v[96:97], v[192:193], v[140:141] op_sel_hi:[1,0,1]
	v_pk_fma_f32 v[94:95], v[94:95], v[192:193], v[138:139] op_sel_hi:[1,0,1]
	v_pk_fma_f32 v[92:93], v[92:93], v[192:193], v[132:133] op_sel_hi:[1,0,1]
	v_pk_fma_f32 v[90:91], v[90:91], v[192:193], v[130:131] op_sel_hi:[1,0,1]
	v_pk_fma_f32 v[80:81], v[80:81], v[192:193], v[144:145] op_sel_hi:[1,0,1]
	v_pk_fma_f32 v[78:79], v[78:79], v[192:193], v[142:143] op_sel_hi:[1,0,1]
	v_max_f32_e32 v80, 0, v80
	v_max_f32_e32 v78, 0, v78
	v_max_f32_e32 v79, 0, v79
	v_max_f32_e32 v81, 0, v81
	v_max_f32_e32 v110, 0, v110
	v_max_f32_e32 v111, 0, v111
	v_max_f32_e32 v112, 0, v112
	v_max_f32_e32 v113, 0, v113
	v_mul_f32_e32 v192, v80, v80
	v_pk_mul_f32 v[110:111], v[110:111], v[110:111]
	v_pk_mul_f32 v[112:113], v[112:113], v[112:113]
	v_pk_fma_f32 v[84:85], v[84:85], v[178:179], v[132:133] op_sel_hi:[1,0,1]
	v_max_f32_e32 v94, 0, v94
	v_max_f32_e32 v90, 0, v90
	v_max_f32_e32 v95, 0, v95
	v_max_f32_e32 v91, 0, v91
	v_max_f32_e32 v96, 0, v96
	v_max_f32_e32 v92, 0, v92
	v_max_f32_e32 v97, 0, v97
	v_max_f32_e32 v93, 0, v93
	v_pk_fma_f32 v[88:89], v[88:89], v[178:179], v[140:141] op_sel_hi:[1,0,1]
	v_pk_fma_f32 v[86:87], v[86:87], v[178:179], v[138:139] op_sel_hi:[1,0,1]
	v_pk_fma_f32 v[82:83], v[82:83], v[178:179], v[130:131] op_sel_hi:[1,0,1]
	v_max_f32_e32 v85, 0, v85
	v_pk_mul_f32 v[94:95], v[94:95], v[94:95]
	v_pk_mul_f32 v[90:91], v[90:91], v[90:91]
	v_pk_mul_f32 v[96:97], v[96:97], v[96:97]
	v_pk_mul_f32 v[92:93], v[92:93], v[92:93]
	v_pk_fma_f32 v[68:69], v[68:69], v[178:179], v[136:137] op_sel_hi:[1,0,1]
	v_pk_fma_f32 v[66:67], v[66:67], v[178:179], v[134:135] op_sel_hi:[1,0,1]
	v_max_f32_e32 v86, 0, v86
	v_max_f32_e32 v82, 0, v82
	v_max_f32_e32 v87, 0, v87
	v_max_f32_e32 v83, 0, v83
	v_max_f32_e32 v88, 0, v88
	v_max_f32_e32 v84, 0, v84
	v_max_f32_e32 v89, 0, v89
	v_pk_fma_f32 v[72:73], v[72:73], v[178:179], v[144:145] op_sel_hi:[1,0,1]
	v_pk_fma_f32 v[70:71], v[70:71], v[178:179], v[142:143] op_sel_hi:[1,0,1]
	v_max_f32_e32 v66, 0, v66
	v_max_f32_e32 v67, 0, v67
	s_waitcnt vmcnt(1)
	v_mov_b32_e32 v98, v147
	v_mov_b32_e32 v99, v148
	v_mov_b32_e32 v147, v149
	s_waitcnt vmcnt(0)
; __device__ __forceinline__ u32x4 pack8(f32x4 v0, f32x4 v1) { u32x4 w; w.x = cvt_pk_bf16(v0[0], v0[1]); w.y = cvt_pk_bf16(v0[2], v0[3]); w.z = cvt_pk_bf16(v1[0], v1[1]); w.w = cvt_pk_bf16(v1[2], v1[3]); return w; }
; __device__ __forceinline__ float row_rstd16_q(const float* ssqx, int row, int fq) {
;     const f32x4 s0 = *(const f32x4*)(ssqx + (size_t)row * 16 + 4 * fq); float s = (s0[0] + s0[1]) + (s0[2] + s0[3]);
;     { auto r = __builtin_amdgcn_permlane16_swap(__float_as_uint(s), __float_as_uint(s), false, false); s = __uint_as_float(r[0]) + __uint_as_float(r[1]); }
;     { auto r = __builtin_amdgcn_permlane32_swap(__float_as_uint(s), __float_as_uint(s), false, false); s = __uint_as_float(r[0]) + __uint_as_float(r[1]); }
;     return rsqrtf(s * (1.0f / 1024.0f) + 1e-6f);
; }
;     __device__ __forceinline__ void operator()(const f32x4 (&acc)[2][2][4][2], const Unit& u, int wr, int wc, int fr, int fq) const {
;     ...
;             for (int m = 0; m < 4; ++m) { const int row = row0 + ai * HALF + m * 16; bf16_t* rowp = H + (size_t)row * 4096 + col0; const float rs = rsv[ai][m];
; #pragma unroll
;                 for (int bj = 0; bj < 2; ++bj) { f32x4 v0 = acc[ai][bj][m][0] * rs + sw[bj][0], v1 = acc[ai][bj][m][1] * rs + sw[bj][1];
; #pragma unroll
;                     for (int e = 0; e < 4; ++e) { const float a = fmaxf(v0[e], 0.f), b = fmaxf(v1[e], 0.f); v0[e] = a * a; v1[e] = b * b; }
;                     *(u32x4*)(rowp + bj * HALF) = pack8(v0, v1); }
	v_mov_b32_e32 v100, v151
	v_mov_b32_e32 v101, v152
	v_mov_b32_e32 v151, v153
	v_pk_add_f32 v[98:99], v[98:99], v[146:147]
	v_pk_add_f32 v[100:101], v[100:101], v[150:151]
	v_pk_add_f32 v[98:99], v[98:99], v[98:99] op_sel:[0,1] op_sel_hi:[1,0]
	v_pk_add_f32 v[100:101], v[100:101], v[100:101] op_sel:[0,1] op_sel_hi:[1,0]
	v_mov_b32_e32 v99, v98
	v_mov_b32_e32 v101, v100
	s_nop 0
	v_permlane16_swap_b32_e32 v98, v99
	v_permlane16_swap_b32_e32 v100, v101
	v_add_f32_e32 v99, v98, v99
	v_add_f32_e32 v98, v100, v101
	v_mov_b32_e32 v101, v99
	v_mov_b32_e32 v100, v98
	s_nop 0
	v_permlane32_swap_b32_e32 v99, v101
	v_permlane32_swap_b32_e32 v98, v100
	v_pk_add_f32 v[98:99], v[98:99], v[100:101]
	v_mul_f32_e32 v149, v187, v187
	v_pk_fma_f32 v[98:99], v[98:99], s[28:29], v[168:169] op_sel_hi:[1,0,0]
	v_mul_f32_e32 v150, v193, v193
	v_mul_f32_e32 v100, 0x4b800000, v99
	v_mul_f32_e32 v101, 0x4b800000, v98
	v_cmp_gt_f32_e32 vcc, s90, v99
	v_cmp_gt_f32_e64 s[44:45], s90, v98
	v_mul_f32_e32 v187, v74, v74
	v_cndmask_b32_e32 v99, v99, v100, vcc
	v_cndmask_b32_e64 v98, v98, v101, s[44:45]
	v_rsq_f32_e32 v99, v99
	v_rsq_f32_e32 v98, v98
	v_mul_f32_e32 v101, v106, v106
	v_mul_f32_e32 v193, v76, v76
	v_mul_f32_e32 v100, 0x45800000, v99
	v_mul_f32_e32 v102, 0x45800000, v98
	v_cndmask_b32_e32 v100, v99, v100, vcc
	v_cndmask_b32_e64 v98, v98, v102, s[44:45]
	global_load_dwordx4 v[102:105], v[190:191], off
	v_mul_f32_e32 v99, v107, v107
	global_load_dwordx4 v[106:109], v[194:195], off
	v_mul_f32_e32 v191, v75, v75
	v_mul_f32_e32 v195, v77, v77
	v_mul_f32_e32 v148, v186, v186
	v_mul_f32_e32 v186, v78, v78
	v_mul_f32_e32 v190, v79, v79
	v_mul_f32_e32 v194, v81, v81
	v_mul_f32_e32 v146, v182, v182
	v_mul_f32_e32 v147, v184, v184
	v_mul_f32_e32 v151, v198, v198
	v_mul_f32_e32 v152, v199, v199
	v_mul_f32_e32 v153, v200, v200
	v_mul_f32_e32 v182, v201, v201
	v_mul_f32_e32 v184, v202, v202
	v_max_f32_e32 v68, 0, v68
	v_pk_mul_f32 v[86:87], v[86:87], v[86:87]
	v_pk_mul_f32 v[82:83], v[82:83], v[82:83]
	v_mul_f32_e32 v88, v88, v88
	v_max_f32_e32 v70, 0, v70
	v_max_f32_e32 v69, 0, v69
	v_pk_fma_f32 v[58:59], v[58:59], v[100:101], v[130:131] op_sel_hi:[1,0,1]
	v_mul_f32_e32 v70, v70, v70
	v_mul_f32_e32 v69, v69, v69
	v_pk_fma_f32 v[62:63], v[62:63], v[100:101], v[138:139] op_sel_hi:[1,0,1]
	v_pk_fma_f32 v[60:61], v[60:61], v[100:101], v[132:133] op_sel_hi:[1,0,1]
	v_max_f32_e32 v58, 0, v58
	v_pk_fma_f32 v[64:65], v[64:65], v[100:101], v[140:141] op_sel_hi:[1,0,1]
	v_max_f32_e32 v59, 0, v59
	v_max_f32_e32 v60, 0, v60
	v_max_f32_e32 v62, 0, v62
	v_max_f32_e32 v61, 0, v61
	v_pk_fma_f32 v[52:53], v[52:53], v[100:101], v[136:137] op_sel_hi:[1,0,1]
	v_pk_fma_f32 v[50:51], v[50:51], v[100:101], v[134:135] op_sel_hi:[1,0,1]
	v_mul_f32_e32 v62, v62, v62
	v_mul_f32_e32 v61, v61, v61
	v_pk_fma_f32 v[56:57], v[56:57], v[100:101], v[144:145] op_sel_hi:[1,0,1]
	v_pk_fma_f32 v[54:55], v[54:55], v[100:101], v[142:143] op_sel_hi:[1,0,1]
	v_max_f32_e32 v50, 0, v50
	v_max_f32_e32 v51, 0, v51
	v_max_f32_e32 v52, 0, v52
	v_max_f32_e32 v54, 0, v54
	v_max_f32_e32 v53, 0, v53
	v_pk_fma_f32 v[42:43], v[42:43], v[98:99], v[130:131] op_sel_hi:[1,0,1]
	v_mul_f32_e32 v54, v54, v54
	v_mul_f32_e32 v53, v53, v53
	v_pk_fma_f32 v[46:47], v[46:47], v[98:99], v[138:139] op_sel_hi:[1,0,1]
	v_pk_fma_f32 v[44:45], v[44:45], v[98:99], v[132:133] op_sel_hi:[1,0,1]
	v_max_f32_e32 v42, 0, v42
	v_pk_fma_f32 v[48:49], v[48:49], v[98:99], v[140:141] op_sel_hi:[1,0,1]
	v_max_f32_e32 v43, 0, v43
	v_max_f32_e32 v44, 0, v44
	v_max_f32_e32 v46, 0, v46
	v_max_f32_e32 v45, 0, v45
	v_pk_fma_f32 v[36:37], v[36:37], v[98:99], v[136:137] op_sel_hi:[1,0,1]
	v_pk_fma_f32 v[34:35], v[34:35], v[98:99], v[134:135] op_sel_hi:[1,0,1]
	v_mul_f32_e32 v46, v46, v46
	v_mul_f32_e32 v45, v45, v45
	v_pk_fma_f32 v[40:41], v[40:41], v[98:99], v[144:145] op_sel_hi:[1,0,1]
	v_pk_fma_f32 v[38:39], v[38:39], v[98:99], v[142:143] op_sel_hi:[1,0,1]
	v_max_f32_e32 v34, 0, v34
	v_max_f32_e32 v35, 0, v35
	v_max_f32_e32 v36, 0, v36
	v_max_f32_e32 v38, 0, v38
	v_max_f32_e32 v37, 0, v37
	v_mul_f32_e32 v38, v38, v38
	v_mul_f32_e32 v37, v37, v37
	s_waitcnt vmcnt(1)
	v_mov_b32_e32 v74, v103
	v_mov_b32_e32 v75, v104
	v_mov_b32_e32 v103, v105
	s_waitcnt vmcnt(0)
	v_mov_b32_e32 v76, v107
	v_mov_b32_e32 v77, v108
	v_mov_b32_e32 v107, v109
	v_pk_add_f32 v[74:75], v[74:75], v[102:103]
	v_pk_add_f32 v[76:77], v[76:77], v[106:107]
	v_pk_add_f32 v[74:75], v[74:75], v[74:75] op_sel:[0,1] op_sel_hi:[1,0]
	v_pk_add_f32 v[76:77], v[76:77], v[76:77] op_sel:[0,1] op_sel_hi:[1,0]
	v_mov_b32_e32 v75, v74
	v_mov_b32_e32 v77, v76
	s_nop 0
	v_permlane16_swap_b32_e32 v74, v75
	v_permlane16_swap_b32_e32 v76, v77
	v_add_f32_e32 v75, v74, v75
	v_add_f32_e32 v74, v76, v77
	v_mov_b32_e32 v77, v75
	v_mov_b32_e32 v76, v74
	s_nop 0
	v_permlane32_swap_b32_e32 v75, v77
	v_permlane32_swap_b32_e32 v74, v76
	v_pk_add_f32 v[74:75], v[74:75], v[76:77]
	s_nop 0
	v_pk_fma_f32 v[74:75], v[74:75], s[28:29], v[168:169] op_sel_hi:[1,0,0]
	s_nop 0
	v_mul_f32_e32 v76, 0x4b800000, v75
	v_mul_f32_e32 v77, 0x4b800000, v74
	v_cmp_gt_f32_e32 vcc, s90, v75
	v_cmp_gt_f32_e64 s[44:45], s90, v74
	s_nop 0
	v_cndmask_b32_e32 v75, v75, v76, vcc
	v_cndmask_b32_e64 v74, v74, v77, s[44:45]
	v_rsq_f32_e32 v75, v75
	v_rsq_f32_e32 v74, v74
	v_mul_f32_e32 v77, v84, v84
	v_mul_f32_e32 v84, v89, v89
	v_mul_f32_e32 v76, 0x45800000, v75
	v_mul_f32_e32 v78, 0x45800000, v74
	v_cndmask_b32_e32 v76, v75, v76, vcc
	v_cndmask_b32_e64 v74, v74, v78, s[44:45]
	v_cvt_pk_bf16_f32 v78, v126, v127
	v_cvt_pk_bf16_f32 v79, v128, v129
	v_cvt_pk_bf16_f32 v80, v122, v123
	v_cvt_pk_bf16_f32 v81, v124, v125
	global_store_dwordx4 v[196:197], v[78:81], off
; __device__ __forceinline__ u32x4 pack8(f32x4 v0, f32x4 v1) { u32x4 w; w.x = cvt_pk_bf16(v0[0], v0[1]); w.y = cvt_pk_bf16(v0[2], v0[3]); w.z = cvt_pk_bf16(v1[0], v1[1]); w.w = cvt_pk_bf16(v1[2], v1[3]); return w; }
;     __device__ __forceinline__ void operator()(const f32x4 (&acc)[2][2][4][2], const Unit& u, int wr, int wc, int fr, int fq) const {
;     ...
;             for (int m = 0; m < 4; ++m) { const int row = row0 + ai * HALF + m * 16; bf16_t* rowp = H + (size_t)row * 4096 + col0; const float rs = rsv[ai][m];
; #pragma unroll
;                 for (int bj = 0; bj < 2; ++bj) { f32x4 v0 = acc[ai][bj][m][0] * rs + sw[bj][0], v1 = acc[ai][bj][m][1] * rs + sw[bj][1];
; #pragma unroll
;                     for (int e = 0; e < 4; ++e) { const float a = fmaxf(v0[e], 0.f), b = fmaxf(v1[e], 0.f); v0[e] = a * a; v1[e] = b * b; }
;                     *(u32x4*)(rowp + bj * HALF) = pack8(v0, v1); }
	v_mul_f32_e32 v75, v85, v85
	v_pk_fma_f32 v[26:27], v[26:27], v[76:77], v[130:131] op_sel_hi:[1,0,1]
	v_cvt_pk_bf16_f32 v78, v110, v111
	v_cvt_pk_bf16_f32 v79, v112, v113
	v_cvt_pk_bf16_f32 v80, v101, v99
	v_cvt_pk_bf16_f32 v81, v146, v147
	global_store_dwordx4 v[196:197], v[78:81], off offset:256
	v_pk_fma_f32 v[30:31], v[30:31], v[76:77], v[138:139] op_sel_hi:[1,0,1]
	v_pk_fma_f32 v[28:29], v[28:29], v[76:77], v[132:133] op_sel_hi:[1,0,1]
	v_cvt_pk_bf16_f32 v78, v118, v119
	v_cvt_pk_bf16_f32 v79, v120, v121
	v_cvt_pk_bf16_f32 v80, v114, v115
	v_cvt_pk_bf16_f32 v81, v116, v117
	global_store_dwordx4 v[188:189], v[78:81], off
	v_max_f32_e32 v26, 0, v26
	v_pk_fma_f32 v[32:33], v[32:33], v[76:77], v[140:141] op_sel_hi:[1,0,1]
	v_cvt_pk_bf16_f32 v78, v148, v150
	v_cvt_pk_bf16_f32 v79, v152, v182
	v_cvt_pk_bf16_f32 v80, v149, v151
	v_cvt_pk_bf16_f32 v81, v153, v184
	global_store_dwordx4 v[188:189], v[78:81], off offset:256
	v_max_f32_e32 v27, 0, v27
	v_max_f32_e32 v28, 0, v28
	v_cvt_pk_bf16_f32 v78, v94, v95
	v_cvt_pk_bf16_f32 v79, v96, v97
	v_cvt_pk_bf16_f32 v80, v90, v91
	v_cvt_pk_bf16_f32 v81, v92, v93
	global_store_dwordx4 v[180:181], v[78:81], off
	v_max_f32_e32 v30, 0, v30
	v_max_f32_e32 v29, 0, v29
	v_cvt_pk_bf16_f32 v78, v186, v190
	v_cvt_pk_bf16_f32 v79, v192, v194
	v_cvt_pk_bf16_f32 v80, v187, v191
	v_cvt_pk_bf16_f32 v81, v193, v195
	global_store_dwordx4 v[180:181], v[78:81], off offset:256
	v_pk_fma_f32 v[20:21], v[20:21], v[76:77], v[136:137] op_sel_hi:[1,0,1]
	v_pk_fma_f32 v[18:19], v[18:19], v[76:77], v[134:135] op_sel_hi:[1,0,1]
	v_cvt_pk_bf16_f32 v78, v86, v87
	v_cvt_pk_bf16_f32 v79, v88, v84
	v_cvt_pk_bf16_f32 v80, v82, v83
	v_cvt_pk_bf16_f32 v81, v77, v75
	v_mul_f32_e32 v75, v66, v66
	v_max_f32_e32 v66, 0, v71
	v_mul_f32_e32 v71, v67, v67
	v_max_f32_e32 v67, 0, v72
	v_mul_f32_e32 v72, v68, v68
	v_max_f32_e32 v68, 0, v73
	v_pk_mul_f32 v[66:67], v[66:67], v[66:67]
	v_mul_f32_e32 v68, v68, v68
	global_store_dwordx4 v[176:177], v[78:81], off
	v_cvt_pk_bf16_f32 v66, v70, v66
	v_cvt_pk_bf16_f32 v67, v67, v68
	v_cvt_pk_bf16_f32 v68, v75, v71
	v_cvt_pk_bf16_f32 v69, v72, v69
	global_store_dwordx4 v[176:177], v[66:69], off offset:256
	v_mul_f32_e32 v30, v30, v30
	v_mul_f32_e32 v29, v29, v29
	v_lshlrev_b64 v[66:67], 13, v[174:175]
	v_mul_f32_e32 v68, v58, v58
	v_max_f32_e32 v58, 0, v63
	v_lshl_add_u64 v[66:67], s[50:51], 0, v[66:67]
	v_mul_f32_e32 v58, v58, v58
	v_mul_f32_e32 v63, v59, v59
	v_max_f32_e32 v59, 0, v64
	v_mul_f32_e32 v64, v60, v60
	v_max_f32_e32 v60, 0, v65
	v_lshl_add_u64 v[66:67], v[66:67], 0, v[172:173]
	v_mul_f32_e32 v59, v59, v59
	v_mul_f32_e32 v60, v60, v60
	v_cvt_pk_bf16_f32 v58, v62, v58
	v_cvt_pk_bf16_f32 v59, v59, v60
	v_cvt_pk_bf16_f32 v60, v68, v63
	v_cvt_pk_bf16_f32 v61, v64, v61
	global_store_dwordx4 v[66:67], v[58:61], off
	v_pk_fma_f32 v[24:25], v[24:25], v[76:77], v[144:145] op_sel_hi:[1,0,1]
	v_pk_fma_f32 v[22:23], v[22:23], v[76:77], v[142:143] op_sel_hi:[1,0,1]
	v_mul_f32_e32 v58, v50, v50
	v_max_f32_e32 v50, 0, v55
	v_mul_f32_e32 v55, v51, v51
	v_max_f32_e32 v51, 0, v56
	v_mul_f32_e32 v56, v52, v52
	v_max_f32_e32 v52, 0, v57
	v_pk_mul_f32 v[50:51], v[50:51], v[50:51]
	v_mul_f32_e32 v52, v52, v52
	v_cvt_pk_bf16_f32 v50, v54, v50
	v_cvt_pk_bf16_f32 v51, v51, v52
	v_cvt_pk_bf16_f32 v52, v58, v55
	v_cvt_pk_bf16_f32 v53, v56, v53
	global_store_dwordx4 v[66:67], v[50:53], off offset:256
	v_max_f32_e32 v18, 0, v18
	v_max_f32_e32 v19, 0, v19
	v_lshlrev_b64 v[50:51], 13, v[170:171]
	v_mul_f32_e32 v52, v42, v42
	v_max_f32_e32 v42, 0, v47
	v_lshl_add_u64 v[50:51], s[50:51], 0, v[50:51]
	v_mul_f32_e32 v42, v42, v42
	v_mul_f32_e32 v47, v43, v43
	v_max_f32_e32 v43, 0, v48
	v_mul_f32_e32 v48, v44, v44
	v_max_f32_e32 v44, 0, v49
	v_lshl_add_u64 v[50:51], v[50:51], 0, v[172:173]
	v_mul_f32_e32 v43, v43, v43
; __device__ __forceinline__ u32x4 pack8(f32x4 v0, f32x4 v1) { u32x4 w; w.x = cvt_pk_bf16(v0[0], v0[1]); w.y = cvt_pk_bf16(v0[2], v0[3]); w.z = cvt_pk_bf16(v1[0], v1[1]); w.w = cvt_pk_bf16(v1[2], v1[3]); return w; }
; #define PG8_BAR __builtin_amdgcn_s_barrier()
;     __device__ __forceinline__ void operator()(const f32x4 (&acc)[2][2][4][2], const Unit& u, int wr, int wc, int fr, int fq) const {
;     ...
;             for (int m = 0; m < 4; ++m) { const int row = row0 + ai * HALF + m * 16; bf16_t* rowp = H + (size_t)row * 4096 + col0; const float rs = rsv[ai][m];
; #pragma unroll
;                 for (int bj = 0; bj < 2; ++bj) { f32x4 v0 = acc[ai][bj][m][0] * rs + sw[bj][0], v1 = acc[ai][bj][m][1] * rs + sw[bj][1];
; #pragma unroll
;                     for (int e = 0; e < 4; ++e) { const float a = fmaxf(v0[e], 0.f), b = fmaxf(v1[e], 0.f); v0[e] = a * a; v1[e] = b * b; }
;                     *(u32x4*)(rowp + bj * HALF) = pack8(v0, v1); }
; template <class Epi, class Sched, bool ALIGN_EPI, bool SP2, int KC, int LDAC, int LDBC = KC>
; __device__ __forceinline__ void gemm_phase(PG8_LAS unsigned char* lds, const Gemm g, const Sched& S, const Epi& E, int tid_in) {
;     ...
;         if constexpr (ALIGN_EPI) { if (wr == 0) PG8_BAR; }
;         if constexpr (!Epi::AFTER_DRAIN) { Unit ue = cur; int ln_; asm volatile("v_mbcnt_lo_u32_b32 %0, -1, 0\n\tv_mbcnt_hi_u32_b32 %0, -1, %0" : "=&v"(ln_), "+s"(ue.pm), "+s"(ue.pn)); E(acc, ue, wr, wc, ln_ & 15, ln_ >> 4); S.done(cur); }
;         if (!has_next) break;
; #pragma unroll
;         for (int a = 0; a < 2; ++a)
; #pragma unroll
;             for (int b = 0; b < 2; ++b)
; #pragma unroll
;                 for (int m = 0; m < 4; ++m)
; #pragma unroll
;                     for (int n = 0; n < 2; ++n) acc[a][b][m][n] = (f32x4){0.f, 0.f, 0.f, 0.f};
;         cur = nxt; cA = nA; cB = nB; ++ui;
;         if constexpr (ALIGN_EPI) { if (wr == 1) PG8_BAR; }
	v_mul_f32_e32 v44, v44, v44
	v_cvt_pk_bf16_f32 v42, v46, v42
	v_cvt_pk_bf16_f32 v43, v43, v44
	v_cvt_pk_bf16_f32 v44, v52, v47
	v_cvt_pk_bf16_f32 v45, v48, v45
	global_store_dwordx4 v[50:51], v[42:45], off
	v_max_f32_e32 v20, 0, v20
	v_max_f32_e32 v22, 0, v22
	v_mul_f32_e32 v42, v34, v34
	v_max_f32_e32 v34, 0, v39
	v_mul_f32_e32 v39, v35, v35
	v_max_f32_e32 v35, 0, v40
	v_mul_f32_e32 v40, v36, v36
	v_max_f32_e32 v36, 0, v41
	v_pk_mul_f32 v[34:35], v[34:35], v[34:35]
	v_mul_f32_e32 v36, v36, v36
	v_cvt_pk_bf16_f32 v34, v38, v34
	v_cvt_pk_bf16_f32 v35, v35, v36
	v_cvt_pk_bf16_f32 v36, v42, v39
	v_cvt_pk_bf16_f32 v37, v40, v37
	global_store_dwordx4 v[50:51], v[34:37], off offset:256
	v_max_f32_e32 v21, 0, v21
	v_pk_fma_f32 v[10:11], v[10:11], v[74:75], v[130:131] op_sel_hi:[1,0,1]
	v_lshlrev_b64 v[34:35], 13, v[166:167]
	v_mul_f32_e32 v36, v26, v26
	v_max_f32_e32 v26, 0, v31
	v_lshl_add_u64 v[34:35], s[50:51], 0, v[34:35]
	v_mul_f32_e32 v26, v26, v26
	v_mul_f32_e32 v31, v27, v27
	v_max_f32_e32 v27, 0, v32
	v_mul_f32_e32 v32, v28, v28
	v_max_f32_e32 v28, 0, v33
	v_lshl_add_u64 v[34:35], v[34:35], 0, v[172:173]
	v_mul_f32_e32 v27, v27, v27
	v_mul_f32_e32 v28, v28, v28
	v_cvt_pk_bf16_f32 v26, v30, v26
	v_cvt_pk_bf16_f32 v27, v27, v28
	v_cvt_pk_bf16_f32 v28, v36, v31
	v_cvt_pk_bf16_f32 v29, v32, v29
	global_store_dwordx4 v[34:35], v[26:29], off
	v_mul_f32_e32 v22, v22, v22
	v_mul_f32_e32 v21, v21, v21
	v_mul_f32_e32 v26, v18, v18
	v_max_f32_e32 v18, 0, v23
	v_mul_f32_e32 v23, v19, v19
	v_max_f32_e32 v19, 0, v24
	v_mul_f32_e32 v24, v20, v20
	v_max_f32_e32 v20, 0, v25
	v_pk_mul_f32 v[18:19], v[18:19], v[18:19]
	v_mul_f32_e32 v20, v20, v20
	v_cvt_pk_bf16_f32 v18, v22, v18
	v_cvt_pk_bf16_f32 v19, v19, v20
	v_cvt_pk_bf16_f32 v20, v26, v23
	v_pk_fma_f32 v[14:15], v[14:15], v[74:75], v[138:139] op_sel_hi:[1,0,1]
	v_pk_fma_f32 v[12:13], v[12:13], v[74:75], v[132:133] op_sel_hi:[1,0,1]
	v_max_f32_e32 v10, 0, v10
	v_cvt_pk_bf16_f32 v21, v24, v21
	global_store_dwordx4 v[34:35], v[18:21], off offset:256
	v_pk_fma_f32 v[16:17], v[16:17], v[74:75], v[140:141] op_sel_hi:[1,0,1]
	v_max_f32_e32 v11, 0, v11
	v_lshlrev_b64 v[18:19], 13, v[164:165]
	v_mul_f32_e32 v20, v10, v10
	v_max_f32_e32 v10, 0, v15
	v_max_f32_e32 v12, 0, v12
	v_lshl_add_u64 v[18:19], s[50:51], 0, v[18:19]
	v_max_f32_e32 v14, 0, v14
	v_mul_f32_e32 v10, v10, v10
	v_mul_f32_e32 v15, v11, v11
	v_max_f32_e32 v11, 0, v16
	v_mul_f32_e32 v16, v12, v12
	v_max_f32_e32 v12, 0, v17
	v_max_f32_e32 v13, 0, v13
	v_pk_fma_f32 v[4:5], v[4:5], v[74:75], v[136:137] op_sel_hi:[1,0,1]
	v_pk_fma_f32 v[2:3], v[2:3], v[74:75], v[134:135] op_sel_hi:[1,0,1]
	v_lshl_add_u64 v[18:19], v[18:19], 0, v[172:173]
	v_mul_f32_e32 v14, v14, v14
	v_mul_f32_e32 v11, v11, v11
	v_pk_mul_f32 v[12:13], v[12:13], v[12:13]
	v_cvt_pk_bf16_f32 v10, v14, v10
	v_pk_fma_f32 v[8:9], v[8:9], v[74:75], v[144:145] op_sel_hi:[1,0,1]
	v_pk_fma_f32 v[6:7], v[6:7], v[74:75], v[142:143] op_sel_hi:[1,0,1]
	v_max_f32_e32 v2, 0, v2
	v_max_f32_e32 v3, 0, v3
	v_max_f32_e32 v4, 0, v4
	v_cvt_pk_bf16_f32 v11, v11, v12
	v_cvt_pk_bf16_f32 v12, v20, v15
	v_cvt_pk_bf16_f32 v13, v16, v13
	global_store_dwordx4 v[18:19], v[10:13], off
	v_max_f32_e32 v5, 0, v5
	v_max_f32_e32 v6, 0, v6
	v_mul_f32_e32 v10, v2, v2
	v_max_f32_e32 v2, 0, v7
	v_mul_f32_e32 v7, v3, v3
	v_max_f32_e32 v3, 0, v8
	v_mul_f32_e32 v8, v4, v4
	v_max_f32_e32 v4, 0, v9
	v_pk_mul_f32 v[2:3], v[2:3], v[2:3]
	v_pk_mul_f32 v[4:5], v[4:5], v[4:5]
	v_mul_f32_e32 v6, v6, v6
	v_cvt_pk_bf16_f32 v2, v6, v2
	v_cvt_pk_bf16_f32 v3, v3, v4
	v_cvt_pk_bf16_f32 v4, v10, v7
	v_cvt_pk_bf16_f32 v5, v8, v5
	global_store_dwordx4 v[18:19], v[2:5], off offset:256
	s_andn2_b64 vcc, exec, s[42:43]
	s_mov_b64 s[42:43], -1
	s_cbranch_vccnz .LBB0_109
	s_andn2_b64 vcc, exec, s[22:23]
	s_cbranch_vccnz .LBB0_108
	s_barrier
	s_branch .LBB0_108

; #define SBAR() __builtin_amdgcn_sched_barrier(0)
; template <int KB, bool HASY>
; __device__ __forceinline__ void phaseA(f32x16& X0, f32x16& X1, f32x16& Y0, f32x16& Y1, bf16x8& pa0, bf16x8& pa1, bf16x8& pa2, bf16x8& pa3,
;                                        const bf16x8* qr, const f32x16& negm, int kaddr, VFr& vf, int vb, float& l_reg) {
;   SBAR();
;   float ls = 0.f;
; __device__ __forceinline__ void attn_unit(const bf16_t* __restrict__ Qb, const bf16_t* __restrict__ KNh, const bf16_t* __restrict__ KRb, const bf16_t* __restrict__ Vh,
;                                           bf16_t* __restrict__ Ob, int nkeys, char* lds, int tid_in) {
;     ...
;   float m_reg = 0.f, l_reg = 0.f; f32x16 o[2] = {}; f32x16 negm = {}; bf16x8 qr[6];
;   const bf16_t* Qw = Qb + (long)(wid * QBLK + r32) * 768 + hi * 8;
; #pragma unroll
;   for (int d0 = 0; d0 < 6; ++d0) qr[d0] = *reinterpret_cast<const bf16x8*>(Qw + d0 * 16);
;   const int sr = tid >> 3, sc = (tid & 7) * 8, vst0 = v_st_nat(sr, sc), kst0 = KSWZ(sr, sc * 2);
;   const bool krt = tid < 256; const int rr_ = (tid >> 2) & 63, rc_ = (tid & 3) * 8, kst1 = KSWZ(rr_, 128 + rc_ * 2);
;   const int vb0 = (int)(uintptr_t)V_lds + v_rd_base(lane);
;   const int kaddr = (int)(uintptr_t)K_lds + r32 * 208 + hi * 16;
;   struct { bf16x8 vs, ks, kr; } sr_[2];
;   typedef unsigned v4u_t __attribute__((ext_vector_type(4)));
;   const __amdgpu_buffer_rsrc_t rV = __builtin_amdgcn_make_buffer_rsrc((void*)Vh, 0, LK * 64 * 2, 0x00020000);
;   const __amdgpu_buffer_rsrc_t rK = __builtin_amdgcn_make_buffer_rsrc((void*)KNh, 0, LK * 64 * 2, 0x00020000);
;   const __amdgpu_buffer_rsrc_t rR = __builtin_amdgcn_make_buffer_rsrc((void*)KRb, 0, LK * 32 * 2, 0x00020000);
;   const int goff_kv = (sr * 64 + sc) * 2, goff_kr = (rr_ * 32 + rc_) * 2;
;     ...
;   f32x16 pA0, pA1, pB0, pB1; float alA, alB; bf16x8 pa0, pa1, pa2, pa3; VFr vf; const int NT = nkeys / KVBLK;
;   constexpr int SE = 0, SO = 1;
;   int vprev = 0, vcur = SHM_V, vnext = 2 * SHM_V;
;     ...
;   SLOAD(SE, 0); asm volatile("s_waitcnt vmcnt(0)" ::: "memory"); SWRITE(0, 0, SE); __syncthreads();
;   phaseA<0, false>(pA0, pA1, pB0, pB1, pa0, pa1, pa2, pa3, qr, negm, kaddr, vf, vb0, l_reg);
;   alA = decide<true>(rowmax32(pA0, pA1), pA0, pA1, m_reg, negm);
;   SLOAD(SO, KVBLK); if (2 < NT) SLOAD(SE, 2 * KVBLK);
;   SWAIT(); SWRITE(1, SHM_V, SO); __syncthreads();
.LBB0_236:
	s_lshr_b32 s29, s28, 3
	s_and_b32 s36, s28, 7
	s_mul_i32 s19, s24, 0x600
	s_mul_hi_u32 s18, s24, 0x600
	s_add_u32 s19, s48, s19
	s_addc_u32 s39, s49, s18
	s_mul_i32 s18, s36, 0xc0
	s_add_u32 s18, s19, s18
	s_addc_u32 s19, s39, 0
	s_mul_hi_u32 s39, s28, 0x108000
	s_mul_i32 s28, s28, 0x108000
	s_add_u32 s44, s5, s28
	s_addc_u32 s40, s8, s39
	s_mul_hi_u32 s41, s29, 0x84000
	s_mul_i32 s29, s29, 0x84000
	s_add_u32 s60, s9, s29
	s_addc_u32 s29, s14, s41
	s_add_u32 s64, s15, s28
	v_mov_b32_e32 v42, v180
	s_addc_u32 s28, s20, s39
	s_movk_i32 s39, 0xffe0
	v_ashrrev_i32_e32 v43, 1, v42
	v_bfe_u32 v181, v42, 5, 1
	v_bfi_b32 v0, s39, v43, v42
	s_waitcnt lgkmcnt(0)
	v_mov_b64_e32 v[2:3], s[18:19]
	v_mad_i64_i32 v[2:3], s[18:19], v0, s78, v[2:3]
	v_lshlrev_b32_e32 v0, 4, v181
	v_lshl_add_u64 v[2:3], v[2:3], 0, v[0:1]
	global_load_dwordx4 v[150:153], v[2:3], off
	global_load_dwordx4 v[146:149], v[2:3], off offset:32
	global_load_dwordx4 v[142:145], v[2:3], off offset:64
	global_load_dwordx4 v[138:141], v[2:3], off offset:96
	global_load_dwordx4 v[134:137], v[2:3], off offset:128
	global_load_dwordx4 v[130:133], v[2:3], off offset:160
	v_lshlrev_b32_e32 v12, 3, v42
	v_and_b32_e32 v13, 56, v12
	v_ashrrev_i32_e32 v11, 3, v42
	v_lshlrev_b32_e32 v10, 1, v13
	s_and_b32 s65, s28, 0xffff
	s_mov_b32 s67, s63
	v_lshl_or_b32 v185, v11, 7, v10
	s_and_b32 s45, s40, 0xffff
	s_mov_b32 s46, s66
	s_mov_b32 s47, s63
	buffer_load_dwordx4 v[6:9], v185, s[64:67], 0 offen
	buffer_load_dwordx4 v[2:5], v185, s[44:47], 0 offen
	s_movk_i32 s18, 0xff
	v_lshlrev_b32_e32 v15, 4, v42
	v_cmp_lt_i32_e32 vcc, s18, v42
	s_movk_i32 s18, 0x100
	v_bfe_u32 v14, v42, 2, 6
	v_and_b32_e32 v44, 48, v15
	v_cmp_gt_i32_e64 s[42:43], s18, v42
	s_and_b32 s61, s29, 0xffff
	v_lshl_or_b32 v186, v14, 6, v44
	s_and_saveexec_b64 s[18:19], s[42:43]
	s_cbranch_execz .LBB0_238
	buffer_load_dwordx4 v[154:157], v186, s[60:63], 0 offen
	buffer_load_dwordx4 v[158:161], v186, s[60:63], s80 offen
.LBB0_238:
	s_or_b64 exec, exec, s[18:19]
	buffer_load_dwordx4 v[204:207], v185, s[64:67], s81 offen
	buffer_load_dwordx4 v[208:211], v185, s[44:47], s81 offen
	buffer_load_dwordx4 v[162:165], v185, s[64:67], s82 offen
	buffer_load_dwordx4 v[166:169], v185, s[44:47], s82 offen
	v_lshrrev_b32_e32 v15, 5, v42
	v_lshrrev_b32_e32 v13, 5, v13
	s_mov_b32 s18, 0x7ffffe
	v_and_or_b32 v13, v15, s18, v13
	v_lshlrev_b32_e32 v15, 5, v11
	v_and_b32_e32 v12, 24, v12
	s_movk_i32 s18, 0xe0
	v_and_or_b32 v12, v15, s18, v12
	v_lshlrev_b32_e32 v12, 1, v12
	s_movk_i32 s18, 0xd0
	s_waitcnt vmcnt(4)
	v_lshl_or_b32 v12, v13, 9, v12
	v_mad_u64_u32 v[10:11], s[18:19], v11, s18, v[10:11]
	v_mul_u32_u24_e32 v45, 0xd0, v14
	v_add_u32_e32 v187, 0, v12
	v_add_u32_e32 v188, 0, v10
	s_waitcnt vmcnt(4)
	ds_write_b128 v187, v[6:9]
	s_waitcnt vmcnt(4)
	ds_write_b128 v188, v[2:5] offset:24576
	s_and_saveexec_b64 s[18:19], s[42:43]
	v_add3_u32 v2, v45, v44, 0
	ds_write_b128 v2, v[154:157] offset:24704
	s_or_b64 exec, exec, s[18:19]
	s_add_i32 s18, 0, 0x6000
	v_and_b32_e32 v182, 31, v42
	s_cmp_lg_u32 s18, -1
	v_mul_u32_u24_e32 v2, 0xd0, v182
	s_cselect_b32 s18, s18, 0
	s_mov_b32 s67, s63
	v_add3_u32 v184, v2, s18, v0
	s_waitcnt lgkmcnt(0)
	s_barrier
	ds_read_b128 v[2:5], v184 offset:0
	ds_read_b128 v[6:9], v184 offset:0x1a00
	ds_read_b128 v[34:37], v184 offset:32
	ds_read_b128 v[38:41], v184 offset:0x1a20
	s_nop 0
	s_waitcnt lgkmcnt(0)
	ds_read_b128 v[46:49], v184 offset:64
	ds_read_b128 v[50:53], v184 offset:0x1a40
	ds_read_b128 v[54:57], v184 offset:0x60
	ds_read_b128 v[58:61], v184 offset:0x1a60
	s_nop 0
	v_mfma_f32_32x32x16_bf16 v[18:33], v[2:5], v[150:153], 0
	v_mfma_f32_32x32x16_bf16 v[2:17], v[6:9], v[150:153], 0
	v_mfma_f32_32x32x16_bf16 v[18:33], v[34:37], v[146:149], v[18:33]
	v_mfma_f32_32x32x16_bf16 v[2:17], v[38:41], v[146:149], v[2:17]
	s_waitcnt lgkmcnt(0)
	ds_read_b128 v[34:37], v184 offset:0x80
	ds_read_b128 v[38:41], v184 offset:0x1a80
	ds_read_b128 v[62:65], v184 offset:0xa0
	ds_read_b128 v[66:69], v184 offset:0x1aa0
	s_nop 0
	v_mfma_f32_32x32x16_bf16 v[18:33], v[46:49], v[142:145], v[18:33]
	v_mfma_f32_32x32x16_bf16 v[2:17], v[50:53], v[142:145], v[2:17]
	v_mfma_f32_32x32x16_bf16 v[18:33], v[54:57], v[138:141], v[18:33]
	v_mfma_f32_32x32x16_bf16 v[2:17], v[58:61], v[138:141], v[2:17]
	s_waitcnt lgkmcnt(0)
	s_nop 0
	v_mfma_f32_32x32x16_bf16 v[18:33], v[34:37], v[134:137], v[18:33]
	v_mfma_f32_32x32x16_bf16 v[2:17], v[38:41], v[134:137], v[2:17]
	v_mfma_f32_32x32x16_bf16 v[18:33], v[62:65], v[130:133], v[18:33]
	v_mfma_f32_32x32x16_bf16 v[2:17], v[66:69], v[130:133], v[2:17]
	s_mov_b32 s46, s66
	s_mov_b32 s47, s63
	s_nop 1
	s_nop 6
	v_max_f32_e32 v0, v19, v19
	v_max_f32_e32 v46, v18, v18
	v_max_f32_e32 v0, v46, v0
	v_max3_f32 v46, v20, v21, v3
	v_max3_f32 v0, v0, v2, v4
	v_max3_f32 v0, v0, v5, v22
	v_max3_f32 v46, v46, v24, v25
	v_max3_f32 v0, v0, v23, v6
	v_max3_f32 v46, v46, v8, v9
	v_max3_f32 v0, v0, v7, v26
	v_max3_f32 v46, v46, v28, v29
	v_max3_f32 v0, v0, v27, v10
	v_max3_f32 v46, v46, v12, v13
	v_max3_f32 v0, v0, v11, v30
	v_max3_f32 v46, v46, v32, v33
	v_max3_f32 v0, v0, v31, v14
	v_max3_f32 v46, v46, v16, v17
	v_max3_f32 v0, v0, v15, v46
	v_mov_b32_e32 v46, v0
	s_nop 1
	v_permlane32_swap_b32_e32 v0, v46
	s_and_saveexec_b64 s[18:19], s[42:43]
	s_cbranch_execz .LBB0_244
	buffer_load_dwordx4 v[154:157], v186, s[60:63], s81 offen
; #define SLOAD(i, k0) do { sr_[i].vs = BLD(rV, goff_kv, (k0) * 128); sr_[i].ks = BLD(rK, goff_kv, (k0) * 128); if (krt) sr_[i].kr = BLD(rR, goff_kr, (k0) * 64); } while (0)
; #define SWRITE(b, voff, i) do { *(bf16x8*)(V_lds + (voff) + vst0) = sr_[i].vs; *(bf16x8*)(K_lds + (b) * SHM_K + kst0) = sr_[i].ks; \
;     if (krt) *(bf16x8*)(K_lds + (b) * SHM_K + kst1) = sr_[i].kr; } while (0)
; #define SWAIT() do { asm volatile("s_waitcnt vmcnt(3)" ::: "memory"); } while (0)
; template <bool FIRST>
; __device__ __forceinline__ float decide(float pmax, f32x16& p0, f32x16& p1, float& m_reg, f32x16& negm) {
;   float alpha = 1.f;
;   if (FIRST || __builtin_expect(__any(pmax > THR2), 0)) {
;     const float dl = FIRST ? pmax : __builtin_fmaxf(pmax, 0.f); m_reg += dl;
; #pragma unroll
;     for (int r = 0; r < 16; ++r) { p0[r] -= dl; p1[r] -= dl; }
; #pragma unroll
;     for (int r = 0; r < 16; ++r) negm[r] = -m_reg;
;     if (!FIRST) alpha = __builtin_amdgcn_exp2f(-dl);
;   }
;   return alpha;
; __device__ __forceinline__ void attn_unit(const bf16_t* __restrict__ Qb, const bf16_t* __restrict__ KNh, const bf16_t* __restrict__ KRb, const bf16_t* __restrict__ Vh,
;                                           bf16_t* __restrict__ Ob, int nkeys, char* lds, int tid_in) {
;     ...
;   alA = decide<true>(rowmax32(pA0, pA1), pA0, pA1, m_reg, negm);
;   SLOAD(SO, KVBLK); if (2 < NT) SLOAD(SE, 2 * KVBLK);
;   SWAIT(); SWRITE(1, SHM_V, SO); __syncthreads();
.LBB0_244:
	s_or_b64 exec, exec, s[18:19]
	s_waitcnt vmcnt(3)
	s_waitcnt vmcnt(3)
	ds_write_b128 v187, v[204:207] offset:8192
	s_waitcnt vmcnt(2)
	ds_write_b128 v188, v[208:211] offset:37888
	v_add_u32_e32 v34, v45, v44
	s_and_saveexec_b64 s[18:19], vcc
	s_xor_b64 s[18:19], exec, s[18:19]
	v_add_u32_e32 v34, v45, v44
	s_andn2_saveexec_b64 s[18:19], s[18:19]
	v_add_u32_e32 v35, 0, v34
	ds_write_b128 v35, v[158:161] offset:38016
	s_or_b64 exec, exec, s[18:19]
	v_max_f32_e32 v36, v46, v46
	v_max_f32_e32 v0, v0, v0
	v_and_b32_e32 v35, 63, v42
	v_max_f32_e32 v0, v0, v36
	v_sub_f32_e32 v67, v3, v0
	v_lshlrev_b32_e32 v3, 4, v35
	v_sub_f32_e32 v68, v4, v0
	v_sub_f32_e32 v66, v2, v0
	v_lshlrev_b32_e32 v2, 3, v35
	v_and_b32_e32 v3, 0xc0, v3
	v_lshlrev_b32_e32 v4, 1, v35
	v_add_f32_e32 v189, 0, v0
	v_sub_f32_e32 v97, v33, v0
	v_sub_f32_e32 v96, v32, v0
	v_sub_f32_e32 v95, v31, v0
	v_sub_f32_e32 v94, v30, v0
	v_sub_f32_e32 v93, v29, v0
	v_sub_f32_e32 v92, v28, v0
	v_sub_f32_e32 v91, v27, v0
	v_sub_f32_e32 v90, v26, v0
	v_sub_f32_e32 v89, v25, v0
	v_sub_f32_e32 v88, v24, v0
	v_sub_f32_e32 v87, v23, v0
	v_sub_f32_e32 v86, v22, v0
	v_sub_f32_e32 v85, v21, v0
	v_sub_f32_e32 v84, v20, v0
	v_sub_f32_e32 v83, v19, v0
	v_sub_f32_e32 v82, v18, v0
	v_sub_f32_e32 v81, v17, v0
	v_sub_f32_e32 v80, v16, v0
	v_sub_f32_e32 v79, v15, v0
	v_sub_f32_e32 v78, v14, v0
	v_sub_f32_e32 v77, v13, v0
	v_sub_f32_e32 v76, v12, v0
	v_sub_f32_e32 v75, v11, v0
	v_sub_f32_e32 v74, v10, v0
	v_sub_f32_e32 v73, v9, v0
	v_sub_f32_e32 v72, v8, v0
	v_sub_f32_e32 v71, v7, v0
	v_sub_f32_e32 v70, v6, v0
	v_sub_f32_e32 v69, v5, v0
	v_and_b32_e32 v0, 0x3fffffc0, v42
	v_and_or_b32 v3, v2, 24, v3
	v_and_b32_e32 v4, 32, v4
	v_and_b32_e32 v2, 0x100, v2
	s_cmp_lg_u32 0, -1
	v_lshl_add_u32 v0, v0, 2, 0
	v_or3_b32 v2, v3, v4, v2
	s_cselect_b32 s19, 0, 0
	v_mov_b32_e32 v14, v1
	v_mov_b32_e32 v15, v1
	v_add_u32_e32 v192, s19, v2
	v_lshl_add_u32 v183, v182, 2, v0
	v_lshl_add_u32 v179, v181, 4, v0
	v_mov_b32_e32 v0, v1
	v_mov_b32_e32 v2, v1
	v_mov_b32_e32 v3, v1
	v_mov_b32_e32 v4, v1
	v_mov_b32_e32 v5, v1
	v_mov_b32_e32 v6, v1
	v_mov_b32_e32 v7, v1
	v_mov_b32_e32 v8, v1
	v_mov_b32_e32 v9, v1
	v_mov_b32_e32 v10, v1
	v_mov_b32_e32 v11, v1
	v_mov_b32_e32 v12, v1
	v_mov_b32_e32 v13, v1
	v_mov_b64_e32 v[32:33], v[14:15]
	v_xor_b32_e32 v50, 0x80000000, v189
	v_mov_b64_e32 v[30:31], v[12:13]
	v_mov_b64_e32 v[28:29], v[10:11]
	v_mov_b64_e32 v[26:27], v[8:9]
	v_mov_b64_e32 v[24:25], v[6:7]
	v_mov_b64_e32 v[22:23], v[4:5]
	v_mov_b64_e32 v[20:21], v[2:3]
	v_mov_b64_e32 v[18:19], v[0:1]
	v_mov_b64_e32 v[16:17], v[14:15]
	v_and_b32_e32 v178, 0xffffffe0, v43
	s_mov_b32 s39, 4
	s_mov_b32 s18, 0
	v_cmp_gt_u32_e64 s[40:41], 32, v35
	v_mov_b32_e32 v194, 0
	s_movk_i32 s53, 0x2000
	s_mov_b32 s52, 0x8000
	s_movk_i32 s68, 0x4000
	v_add_u32_e32 v193, 0, v34
	v_mov_b64_e32 v[14:15], v[12:13]
	v_mov_b64_e32 v[12:13], v[10:11]
	v_mov_b64_e32 v[10:11], v[8:9]
	v_mov_b64_e32 v[8:9], v[6:7]
	v_mov_b64_e32 v[6:7], v[4:5]
	v_mov_b64_e32 v[4:5], v[2:3]
	v_mov_b64_e32 v[2:3], v[0:1]
	s_movk_i32 s69, 0x4000
	v_mov_b32_e32 v51, v50
	v_mov_b32_e32 v52, v50
	v_mov_b32_e32 v53, v50
	v_mov_b32_e32 v54, v50
	v_mov_b32_e32 v55, v50
	v_mov_b32_e32 v56, v50
	v_mov_b32_e32 v57, v50
	v_mov_b32_e32 v58, v50
	v_mov_b32_e32 v59, v50
	v_mov_b32_e32 v60, v50
	v_mov_b32_e32 v61, v50
	v_mov_b32_e32 v62, v50
	v_mov_b32_e32 v63, v50
	v_mov_b32_e32 v64, v50
	v_mov_b32_e32 v65, v50
	s_mov_b32 s76, s53
	s_mov_b32 s53, s18
	v_add_u32_e32 v0, s53, v192
	v_exp_f32_e32 v82, v82
	v_exp_f32_e32 v195, v83
	v_exp_f32_e32 v84, v84
	v_exp_f32_e32 v196, v85
	v_exp_f32_e32 v83, v86
	v_exp_f32_e32 v85, v87
	v_exp_f32_e32 v86, v88
	v_exp_f32_e32 v87, v89
	s_waitcnt lgkmcnt(0)
	s_cmp_lg_u64 s[42:43], 0
	s_cbranch_scc0 .Lmy_y249
; template <int KB, bool HASY>
; __device__ __forceinline__ void phaseA(f32x16& X0, f32x16& X1, f32x16& Y0, f32x16& Y1, bf16x8& pa0, bf16x8& pa1, bf16x8& pa2, bf16x8& pa3,
;                                        const bf16x8* qr, const f32x16& negm, int kaddr, VFr& vf, int vb, float& l_reg) {
;   SBAR();
;   float ls = 0.f;
;   bf16x8 k0 = rd128<KOFF(KB, 0, 0)>(kaddr), k1 = rd128<KOFF(KB, 1, 0)>(kaddr), k2 = rd128<KOFF(KB, 0, 1)>(kaddr), k3 = rd128<KOFF(KB, 1, 1)>(kaddr);
;   if (HASY) { EXP4(Y0, 0); EXP4(Y0, 4); }
;   SBAR(); WAIT4(k0, k1, k2, k3);
;   bf16x8 k4 = rd128<KOFF(KB, 0, 2)>(kaddr), k5 = rd128<KOFF(KB, 1, 2)>(kaddr), k6 = rd128<KOFF(KB, 0, 3)>(kaddr), k7 = rd128<KOFF(KB, 1, 3)>(kaddr);
;   SBAR();
;   X0 = MF(k0, qr[0], negm); if (HASY) { EXP4(Y0, 8); SUM4(Y0, 0); } SBAR();
;   X1 = MF(k1, qr[0], negm); if (HASY) { EXP4(Y0, 12); SUM4(Y0, 4); } SBAR();
;   X0 = MF(k2, qr[1], X0); if (HASY) { PACK8(Y0, 0, pa0); } SBAR();
;   X1 = MF(k3, qr[1], X1); if (HASY) { EXP4(Y1, 0); SUM4(Y0, 8); } SBAR();
;   WAIT4(k4, k5, k6, k7);
;   bf16x8 k8 = rd128<KOFF(KB, 0, 4)>(kaddr), k9 = rd128<KOFF(KB, 1, 4)>(kaddr), k10 = rd128<KOFF(KB, 0, 5)>(kaddr), k11 = rd128<KOFF(KB, 1, 5)>(kaddr);
;   SBAR();
;   X0 = MF(k4, qr[2], X0); if (HASY) { EXP4(Y1, 4); SUM4(Y0, 12); } SBAR();
;   X1 = MF(k5, qr[2], X1); if (HASY) { PACK8(Y0, 8, pa1); } SBAR();
;   X0 = MF(k6, qr[3], X0); if (HASY) { EXP4(Y1, 8); SUM4(Y1, 0); } SBAR();
;   X1 = MF(k7, qr[3], X1); if (HASY) { EXP4(Y1, 12); SUM4(Y1, 4); } SBAR();
;   WAIT4(k8, k9, k10, k11);
;   SBAR();
;   X0 = MF(k8, qr[4], X0); if (HASY) { PACK8(Y1, 0, pa2); } SBAR();
;   X1 = MF(k9, qr[4], X1); if (HASY) { SUM4(Y1, 8); SUM4(Y1, 12); } SBAR();
;   X0 = MF(k10, qr[5], X0); if (HASY) { PACK8(Y1, 8, pa3); } SBAR();
;   X1 = MF(k11, qr[5], X1); if (HASY) vfr_issue<0>(vf, vb);
;   l_reg += ls;
;   SBAR();
; }
; template <bool HASX>
; __device__ __forceinline__ float phaseB(f32x16* o, bf16x8 pa0, bf16x8 pa1, bf16x8 pa2, bf16x8 pa3, VFr& f, int vb, const f32x16& X0, const f32x16& X1) {
;   SBAR(); VWAIT(f); VFr g; vfr_issue<2>(g, vb); SBAR();
;   float a = 0.f, b = 0.f;
;   o[0] = MF(pa0, PKV(f.a0, f.b0), o[0]); SBAR(); o[1] = MF(pa0, PKV(f.c0, f.d0), o[1]);
;   if (HASX) { a = MX3(X0[0], X0[1], X1[0]); b = MX3(X0[2], X0[3], X1[1]); a = MX3(a, X1[2], X1[3]); b = MX3(b, X0[4], X0[5]); } SBAR();
.LBB0_249:
	s_barrier
	ds_read_b128 v[34:37], v184 offset:0x3400
	ds_read_b128 v[38:41], v184 offset:0x4e00
	ds_read_b128 v[42:45], v184 offset:0x3420
	ds_read_b128 v[46:49], v184 offset:0x4e20
	ds_read_b128 v[170:173], v184 offset:0x3440
	ds_read_b128 v[174:177], v184 offset:0x4e40
	ds_read_b128 v[204:207], v184 offset:0x3460
	ds_read_b128 v[208:211], v184 offset:0x4e60
	s_waitcnt lgkmcnt(7)
	v_mfma_f32_32x32x16_bf16 v[114:129], v[34:37], v[150:153], v[50:65]
	v_exp_f32_e32 v88, v90
	v_exp_f32_e32 v89, v91
	v_exp_f32_e32 v90, v92
	v_exp_f32_e32 v91, v93
	s_waitcnt lgkmcnt(6)
	v_mfma_f32_32x32x16_bf16 v[98:113], v[38:41], v[150:153], v[50:65]
	v_exp_f32_e32 v92, v94
	v_exp_f32_e32 v93, v95
	v_exp_f32_e32 v94, v96
	v_exp_f32_e32 v95, v97
	s_waitcnt lgkmcnt(5)
	v_mfma_f32_32x32x16_bf16 v[114:129], v[42:45], v[146:149], v[114:129]
	v_cvt_pk_bf16_f32 v34, v82, v195
	v_cvt_pk_bf16_f32 v35, v84, v196
	v_cvt_pk_bf16_f32 v36, v83, v85
	v_cvt_pk_bf16_f32 v37, v86, v87
	s_waitcnt lgkmcnt(4)
	v_mfma_f32_32x32x16_bf16 v[98:113], v[46:49], v[146:149], v[98:113]
	v_exp_f32_e32 v96, v66
	v_exp_f32_e32 v97, v67
	v_exp_f32_e32 v197, v68
	v_exp_f32_e32 v198, v69
	ds_read_b128 v[38:41], v184 offset:0x3480
	ds_read_b128 v[66:69], v184 offset:0x4e80
	ds_read_b128 v[212:215], v184 offset:0x34a0
	ds_read_b128 v[216:219], v184 offset:0x4ea0
	s_waitcnt lgkmcnt(4)
	v_mfma_f32_32x32x16_bf16 v[114:129], v[170:173], v[142:145], v[114:129]
	v_exp_f32_e32 v199, v70
	v_exp_f32_e32 v200, v71
	v_exp_f32_e32 v201, v72
	v_exp_f32_e32 v202, v73
	v_mfma_f32_32x32x16_bf16 v[98:113], v[174:177], v[142:145], v[98:113]
	v_cvt_pk_bf16_f32 v42, v88, v89
	v_cvt_pk_bf16_f32 v43, v90, v91
	v_cvt_pk_bf16_f32 v44, v92, v93
	v_cvt_pk_bf16_f32 v45, v94, v95
	v_mfma_f32_32x32x16_bf16 v[114:129], v[204:207], v[138:141], v[114:129]
	v_exp_f32_e32 v203, v74
	v_exp_f32_e32 v204, v75
	v_exp_f32_e32 v205, v76
	v_exp_f32_e32 v206, v77
	v_mfma_f32_32x32x16_bf16 v[98:113], v[208:211], v[138:141], v[98:113]
	v_exp_f32_e32 v207, v78
	v_exp_f32_e32 v208, v79
	v_exp_f32_e32 v209, v80
	v_exp_f32_e32 v210, v81
	s_waitcnt lgkmcnt(0)
	s_nop 0
	v_mfma_f32_32x32x16_bf16 v[114:129], v[38:41], v[134:137], v[114:129]
	v_cvt_pk_bf16_f32 v46, v96, v97
	v_cvt_pk_bf16_f32 v47, v197, v198
	v_cvt_pk_bf16_f32 v48, v199, v200
	v_cvt_pk_bf16_f32 v49, v201, v202
	v_mfma_f32_32x32x16_bf16 v[98:113], v[66:69], v[134:137], v[98:113]
	v_mfma_f32_32x32x16_bf16 v[114:129], v[212:215], v[130:133], v[114:129]
	v_cvt_pk_bf16_f32 v38, v203, v204
	v_cvt_pk_bf16_f32 v39, v205, v206
	v_cvt_pk_bf16_f32 v40, v207, v208
	v_cvt_pk_bf16_f32 v41, v209, v210
	ds_read_b64_tr_b16 v[78:79], v0 offset:0
	ds_read_b64_tr_b16 v[80:81], v0 offset:0x400
	ds_read_b64_tr_b16 v[74:75], v0 offset:0x200
	v_mfma_f32_32x32x16_bf16 v[98:113], v[216:219], v[130:133], v[98:113]
	ds_read_b64_tr_b16 v[76:77], v0 offset:0x600
	ds_read_b64_tr_b16 v[70:71], v0 offset:0x800
	ds_read_b64_tr_b16 v[72:73], v0 offset:0xc00
	ds_read_b64_tr_b16 v[66:67], v0 offset:0xa00
	ds_read_b64_tr_b16 v[68:69], v0 offset:0xe00
	s_add_i32 s18, s52, 0xffffe000
	buffer_load_dwordx4 v[170:173], v185, s[64:67], s18 offen
	buffer_load_dwordx4 v[174:177], v185, s[44:47], s18 offen
	s_add_i32 s28, s68, 0xfffff000
	buffer_load_dwordx4 v[158:161], v186, s[60:63], s28 offen
	ds_read_b64_tr_b16 v[212:213], v0 offset:0x1000
	ds_read_b64_tr_b16 v[214:215], v0 offset:0x1400
	ds_read_b64_tr_b16 v[216:217], v0 offset:0x1200
	ds_read_b64_tr_b16 v[218:219], v0 offset:0x1600
	ds_read_b64_tr_b16 v[220:221], v0 offset:0x1800
	ds_read_b64_tr_b16 v[222:223], v0 offset:0x1c00
	ds_read_b64_tr_b16 v[228:229], v0 offset:0x1a00
	ds_read_b64_tr_b16 v[230:231], v0 offset:0x1e00
	s_waitcnt lgkmcnt(8)
	v_mfma_f32_32x32x16_bf16 v[18:33], v[34:37], v[78:81], v[18:33]
	v_add_f32_e32 v238, v82, v195
	v_add_f32_e32 v239, v84, v196
	v_add_f32_e32 v240, v83, v85
	v_add_f32_e32 v241, v86, v87
	v_add_f32_e32 v238, v238, v239
	v_add_f32_e32 v240, v240, v241
	v_mfma_f32_32x32x16_bf16 v[2:17], v[34:37], v[74:77], v[2:17]
	v_max_f32_e32 v34, v114, v115
	v_max3_f32 v35, v116, v117, v99
	v_max3_f32 v34, v34, v98, v100
	v_max3_f32 v35, v35, v118, v119
	v_mfma_f32_32x32x16_bf16 v[18:33], v[42:45], v[70:73], v[18:33]
	v_max3_f32 v34, v34, v101, v120
	v_max3_f32 v35, v35, v102, v103
	v_add_f32_e32 v238, v240, v238
	v_add_f32_e32 v239, v88, v89
	v_add_f32_e32 v241, v90, v91
	v_mfma_f32_32x32x16_bf16 v[2:17], v[42:45], v[66:69], v[2:17]
	v_max3_f32 v34, v34, v121, v104
	v_max3_f32 v34, v34, v105, v124
	v_max3_f32 v35, v35, v122, v123
	v_add_f32_e32 v239, v239, v241
	v_add_f32_e32 v240, v92, v93
	v_add_f32_e32 v241, v94, v95
	s_waitcnt lgkmcnt(0)
	v_mfma_f32_32x32x16_bf16 v[18:33], v[46:49], v[212:215], v[18:33]
	v_max3_f32 v34, v34, v125, v108
	v_max3_f32 v35, v35, v106, v107
	v_add_f32_e32 v238, v239, v238
	v_add_f32_e32 v240, v240, v241
	s_waitcnt vmcnt(3)
	v_add_u32_e32 v67, s69, v187
	ds_write_b128 v67, v[162:165]
	v_mfma_f32_32x32x16_bf16 v[2:17], v[46:49], v[216:219], v[2:17]
	v_max3_f32 v34, v34, v109, v128
	v_max3_f32 v35, v35, v126, v127
	v_add_f32_e32 v238, v240, v238
	v_add_f32_e32 v239, v96, v97
	v_add_f32_e32 v241, v197, v198
	s_waitcnt vmcnt(2)
	ds_write_b128 v188, v[166:169] offset:24576
	v_mfma_f32_32x32x16_bf16 v[18:33], v[38:41], v[220:223], v[18:33]
	v_max3_f32 v34, v34, v129, v112
	v_max3_f32 v35, v35, v110, v111
	v_add_f32_e32 v239, v239, v241
	v_add_f32_e32 v240, v199, v200
	v_add_f32_e32 v241, v201, v202
	ds_write_b128 v193, v[154:157] offset:24704
	v_add_f32_e32 v238, v239, v238
	v_add_f32_e32 v240, v240, v241
	v_mfma_f32_32x32x16_bf16 v[2:17], v[38:41], v[228:231], v[2:17]
	v_max3_f32 v34, v34, v113, v35
	v_cmp_lt_f32_e32 vcc, s35, v34
	v_add_f32_e32 v238, v240, v238
	v_add_f32_e32 v239, v203, v204
	v_add_f32_e32 v241, v205, v206
	v_add_f32_e32 v239, v239, v241
	v_add_f32_e32 v240, v207, v208
	v_add_f32_e32 v241, v209, v210
	v_add_f32_e32 v238, v239, v238
	v_add_f32_e32 v240, v240, v241
	v_add_f32_e32 v238, v240, v238
	v_add_f32_e32 v194, v194, v238
	s_cbranch_vccnz .LBB0_272

; #define SBAR() __builtin_amdgcn_sched_barrier(0)
; #define MX3(a, b, c) __builtin_fmaxf(__builtin_fmaxf((a), (b)), (c))
; #define MF(A, B, C) __builtin_amdgcn_mfma_f32_32x32x16_bf16(A, B, C, 0, 0, 0)
; #define VWAIT(f) asm volatile("s_waitcnt lgkmcnt(0)" : "+v"(f.a0), "+v"(f.b0), "+v"(f.c0), "+v"(f.d0), "+v"(f.a1), "+v"(f.b1), "+v"(f.c1), "+v"(f.d1) :: "memory")
; template <bool HASX>
; __device__ __forceinline__ float phaseB(f32x16* o, bf16x8 pa0, bf16x8 pa1, bf16x8 pa2, bf16x8 pa3, VFr& f, int vb, const f32x16& X0, const f32x16& X1) {
;   SBAR(); VWAIT(f); VFr g; vfr_issue<2>(g, vb); SBAR();
;   float a = 0.f, b = 0.f;
;   o[0] = MF(pa0, PKV(f.a0, f.b0), o[0]); SBAR(); o[1] = MF(pa0, PKV(f.c0, f.d0), o[1]);
;   if (HASX) { a = MX3(X0[0], X0[1], X1[0]); b = MX3(X0[2], X0[3], X1[1]); a = MX3(a, X1[2], X1[3]); b = MX3(b, X0[4], X0[5]); } SBAR();
;   o[0] = MF(pa1, PKV(f.a1, f.b1), o[0]); if (HASX) { a = MX3(a, X0[6], X0[7]); b = MX3(b, X1[4], X1[5]); } SBAR();
;   o[1] = MF(pa1, PKV(f.c1, f.d1), o[1]); if (HASX) { a = MX3(a, X1[6], X1[7]); b = MX3(b, X0[8], X0[9]); a = MX3(a, X0[10], X0[11]); } SBAR();
;   VWAIT(g); SBAR();
;   o[0] = MF(pa2, PKV(g.a0, g.b0), o[0]); if (HASX) { b = MX3(b, X1[8], X1[9]); a = MX3(a, X1[10], X1[11]); } SBAR();
;   o[1] = MF(pa2, PKV(g.c0, g.d0), o[1]); if (HASX) { b = MX3(b, X0[12], X0[13]); a = MX3(a, X0[14], X0[15]); } SBAR();
;   o[0] = MF(pa3, PKV(g.a1, g.b1), o[0]); if (HASX) { b = MX3(b, X1[12], X1[13]); a = MX3(a, X1[14], X1[15]); } SBAR();
;   o[1] = MF(pa3, PKV(g.c1, g.d1), o[1]); SBAR();
.LBB0_263:
	ds_read_b64_tr_b16 v[228:229], v237 offset:0x1000
	ds_read_b64_tr_b16 v[230:231], v237 offset:0x1400
	ds_read_b64_tr_b16 v[238:239], v237 offset:0x1200
	ds_read_b64_tr_b16 v[240:241], v237 offset:0x1600
	ds_read_b64_tr_b16 v[242:243], v237 offset:0x1800
	ds_read_b64_tr_b16 v[244:245], v237 offset:0x1c00
	ds_read_b64_tr_b16 v[246:247], v237 offset:0x1a00
	ds_read_b64_tr_b16 v[248:249], v237 offset:0x1e00
	s_waitcnt lgkmcnt(8)
	v_mfma_f32_32x32x16_bf16 v[18:33], v[114:117], v[126:129], v[18:33]
	v_add_f32_e32 v34, v195, v197
	v_add_f32_e32 v35, v198, v201
	v_add_f32_e32 v36, v196, v199
	v_add_f32_e32 v37, v200, v202
	v_add_f32_e32 v34, v34, v35
	v_add_f32_e32 v36, v36, v37
	v_mfma_f32_32x32x16_bf16 v[2:17], v[114:117], v[122:125], v[2:17]
	v_max_f32_e32 v114, v82, v83
	v_max3_f32 v115, v84, v85, v67
	v_max3_f32 v114, v114, v66, v68
	v_max3_f32 v115, v115, v86, v87
	v_mfma_f32_32x32x16_bf16 v[18:33], v[102:105], v[118:121], v[18:33]
	v_max3_f32 v114, v114, v69, v88
	v_max3_f32 v115, v115, v70, v71
	v_add_f32_e32 v34, v36, v34
	v_add_f32_e32 v35, v203, v204
	v_add_f32_e32 v37, v205, v206
	v_mfma_f32_32x32x16_bf16 v[2:17], v[102:105], v[110:113], v[2:17]
	v_max3_f32 v102, v114, v89, v72
	v_max3_f32 v103, v115, v90, v91
	v_max3_f32 v102, v102, v73, v92
	v_add_f32_e32 v35, v35, v37
	v_add_f32_e32 v36, v207, v208
	v_add_f32_e32 v37, v209, v210
	s_waitcnt lgkmcnt(0)
	v_mfma_f32_32x32x16_bf16 v[18:33], v[106:109], v[228:231], v[18:33]
	v_max3_f32 v103, v103, v74, v75
	v_max3_f32 v102, v102, v93, v76
	v_add_f32_e32 v34, v35, v34
	v_add_f32_e32 v36, v36, v37
	s_cmp_ge_u32 s39, s38
	s_cbranch_scc0 .Lmy_h1w
	s_waitcnt vmcnt(0)

; template <int KB, bool HASY>
; __device__ __forceinline__ void phaseA(f32x16& X0, f32x16& X1, f32x16& Y0, f32x16& Y1, bf16x8& pa0, bf16x8& pa1, bf16x8& pa2, bf16x8& pa3,
;                                        const bf16x8* qr, const f32x16& negm, int kaddr, VFr& vf, int vb, float& l_reg) {
;   SBAR();
;   float ls = 0.f;
;   bf16x8 k0 = rd128<KOFF(KB, 0, 0)>(kaddr), k1 = rd128<KOFF(KB, 1, 0)>(kaddr), k2 = rd128<KOFF(KB, 0, 1)>(kaddr), k3 = rd128<KOFF(KB, 1, 1)>(kaddr);
;   if (HASY) { EXP4(Y0, 0); EXP4(Y0, 4); }
;   SBAR(); WAIT4(k0, k1, k2, k3);
;   bf16x8 k4 = rd128<KOFF(KB, 0, 2)>(kaddr), k5 = rd128<KOFF(KB, 1, 2)>(kaddr), k6 = rd128<KOFF(KB, 0, 3)>(kaddr), k7 = rd128<KOFF(KB, 1, 3)>(kaddr);
;   SBAR();
;   X0 = MF(k0, qr[0], negm); if (HASY) { EXP4(Y0, 8); SUM4(Y0, 0); } SBAR();
;   X1 = MF(k1, qr[0], negm); if (HASY) { EXP4(Y0, 12); SUM4(Y0, 4); } SBAR();
;   X0 = MF(k2, qr[1], X0); if (HASY) { PACK8(Y0, 0, pa0); } SBAR();
;   X1 = MF(k3, qr[1], X1); if (HASY) { EXP4(Y1, 0); SUM4(Y0, 8); } SBAR();
;   WAIT4(k4, k5, k6, k7);
;   bf16x8 k8 = rd128<KOFF(KB, 0, 4)>(kaddr), k9 = rd128<KOFF(KB, 1, 4)>(kaddr), k10 = rd128<KOFF(KB, 0, 5)>(kaddr), k11 = rd128<KOFF(KB, 1, 5)>(kaddr);
;   SBAR();
;   X0 = MF(k4, qr[2], X0); if (HASY) { EXP4(Y1, 4); SUM4(Y0, 12); } SBAR();
;   X1 = MF(k5, qr[2], X1); if (HASY) { PACK8(Y0, 8, pa1); } SBAR();
;   X0 = MF(k6, qr[3], X0); if (HASY) { EXP4(Y1, 8); SUM4(Y1, 0); } SBAR();
;   X1 = MF(k7, qr[3], X1); if (HASY) { EXP4(Y1, 12); SUM4(Y1, 4); } SBAR();
;   WAIT4(k8, k9, k10, k11);
;   SBAR();
;   X0 = MF(k8, qr[4], X0); if (HASY) { PACK8(Y1, 0, pa2); } SBAR();
;   X1 = MF(k9, qr[4], X1); if (HASY) { SUM4(Y1, 8); SUM4(Y1, 12); } SBAR();
;   X0 = MF(k10, qr[5], X0); if (HASY) { PACK8(Y1, 8, pa3); } SBAR();
;   X1 = MF(k11, qr[5], X1); if (HASY) vfr_issue<0>(vf, vb);
;   l_reg += ls;
;   SBAR();
; }
; template <bool HASX>
; __device__ __forceinline__ float phaseB(f32x16* o, bf16x8 pa0, bf16x8 pa1, bf16x8 pa2, bf16x8 pa3, VFr& f, int vb, const f32x16& X0, const f32x16& X1) {
;   SBAR(); VWAIT(f); VFr g; vfr_issue<2>(g, vb); SBAR();
;   float a = 0.f, b = 0.f;
;   o[0] = MF(pa0, PKV(f.a0, f.b0), o[0]); SBAR(); o[1] = MF(pa0, PKV(f.c0, f.d0), o[1]);
;   if (HASX) { a = MX3(X0[0], X0[1], X1[0]); b = MX3(X0[2], X0[3], X1[1]); a = MX3(a, X1[2], X1[3]); b = MX3(b, X0[4], X0[5]); } SBAR();
.Lmy_y249:
	s_barrier
	ds_read_b128 v[34:37], v184 offset:0x3400
	ds_read_b128 v[38:41], v184 offset:0x4e00
	ds_read_b128 v[42:45], v184 offset:0x3420
	ds_read_b128 v[46:49], v184 offset:0x4e20
	ds_read_b128 v[170:173], v184 offset:0x3440
	ds_read_b128 v[174:177], v184 offset:0x4e40
	ds_read_b128 v[204:207], v184 offset:0x3460
	ds_read_b128 v[208:211], v184 offset:0x4e60
	s_waitcnt lgkmcnt(7)
	v_mfma_f32_32x32x16_bf16 v[114:129], v[34:37], v[150:153], v[50:65]
	v_exp_f32_e32 v88, v90
	v_exp_f32_e32 v89, v91
	v_exp_f32_e32 v90, v92
	v_exp_f32_e32 v91, v93
	s_waitcnt lgkmcnt(6)
	v_mfma_f32_32x32x16_bf16 v[98:113], v[38:41], v[150:153], v[50:65]
	v_exp_f32_e32 v92, v94
	v_exp_f32_e32 v93, v95
	v_exp_f32_e32 v94, v96
	v_exp_f32_e32 v95, v97
	s_waitcnt lgkmcnt(5)
	v_mfma_f32_32x32x16_bf16 v[114:129], v[42:45], v[146:149], v[114:129]
	v_cvt_pk_bf16_f32 v34, v82, v195
	v_cvt_pk_bf16_f32 v35, v84, v196
	v_cvt_pk_bf16_f32 v36, v83, v85
	v_cvt_pk_bf16_f32 v37, v86, v87
	s_waitcnt lgkmcnt(4)
	v_mfma_f32_32x32x16_bf16 v[98:113], v[46:49], v[146:149], v[98:113]
	v_exp_f32_e32 v96, v66
	v_exp_f32_e32 v97, v67
	v_exp_f32_e32 v197, v68
	v_exp_f32_e32 v198, v69
	ds_read_b128 v[38:41], v184 offset:0x3480
	ds_read_b128 v[66:69], v184 offset:0x4e80
	ds_read_b128 v[212:215], v184 offset:0x34a0
	ds_read_b128 v[216:219], v184 offset:0x4ea0
	s_waitcnt lgkmcnt(4)
	v_mfma_f32_32x32x16_bf16 v[114:129], v[170:173], v[142:145], v[114:129]
	v_exp_f32_e32 v199, v70
	v_exp_f32_e32 v200, v71
	v_exp_f32_e32 v201, v72
	v_exp_f32_e32 v202, v73
	v_mfma_f32_32x32x16_bf16 v[98:113], v[174:177], v[142:145], v[98:113]
	v_cvt_pk_bf16_f32 v42, v88, v89
	v_cvt_pk_bf16_f32 v43, v90, v91
	v_cvt_pk_bf16_f32 v44, v92, v93
	v_cvt_pk_bf16_f32 v45, v94, v95
	v_mfma_f32_32x32x16_bf16 v[114:129], v[204:207], v[138:141], v[114:129]
	v_exp_f32_e32 v203, v74
	v_exp_f32_e32 v204, v75
	v_exp_f32_e32 v205, v76
	v_exp_f32_e32 v206, v77
	v_mfma_f32_32x32x16_bf16 v[98:113], v[208:211], v[138:141], v[98:113]
	v_exp_f32_e32 v207, v78
	v_exp_f32_e32 v208, v79
	v_exp_f32_e32 v209, v80
	v_exp_f32_e32 v210, v81
	s_waitcnt lgkmcnt(0)
	s_nop 0
	v_mfma_f32_32x32x16_bf16 v[114:129], v[38:41], v[134:137], v[114:129]
	v_cvt_pk_bf16_f32 v46, v96, v97
	v_cvt_pk_bf16_f32 v47, v197, v198
	v_cvt_pk_bf16_f32 v48, v199, v200
	v_cvt_pk_bf16_f32 v49, v201, v202
	v_mfma_f32_32x32x16_bf16 v[98:113], v[66:69], v[134:137], v[98:113]
	v_mfma_f32_32x32x16_bf16 v[114:129], v[212:215], v[130:133], v[114:129]
	v_cvt_pk_bf16_f32 v38, v203, v204
	v_cvt_pk_bf16_f32 v39, v205, v206
	v_cvt_pk_bf16_f32 v40, v207, v208
	v_cvt_pk_bf16_f32 v41, v209, v210
	ds_read_b64_tr_b16 v[78:79], v0 offset:0
	ds_read_b64_tr_b16 v[80:81], v0 offset:0x400
	ds_read_b64_tr_b16 v[74:75], v0 offset:0x200
	v_mfma_f32_32x32x16_bf16 v[98:113], v[216:219], v[130:133], v[98:113]
	ds_read_b64_tr_b16 v[76:77], v0 offset:0x600
	ds_read_b64_tr_b16 v[70:71], v0 offset:0x800
	ds_read_b64_tr_b16 v[72:73], v0 offset:0xc00
	ds_read_b64_tr_b16 v[66:67], v0 offset:0xa00
	ds_read_b64_tr_b16 v[68:69], v0 offset:0xe00
	s_add_i32 s18, s52, 0xffffe000
	buffer_load_dwordx4 v[170:173], v185, s[64:67], s18 offen
	buffer_load_dwordx4 v[174:177], v185, s[44:47], s18 offen
	ds_read_b64_tr_b16 v[212:213], v0 offset:0x1000
	ds_read_b64_tr_b16 v[214:215], v0 offset:0x1400
	ds_read_b64_tr_b16 v[216:217], v0 offset:0x1200
	ds_read_b64_tr_b16 v[218:219], v0 offset:0x1600
	ds_read_b64_tr_b16 v[220:221], v0 offset:0x1800
	ds_read_b64_tr_b16 v[222:223], v0 offset:0x1c00
	ds_read_b64_tr_b16 v[228:229], v0 offset:0x1a00
	ds_read_b64_tr_b16 v[230:231], v0 offset:0x1e00
	s_waitcnt lgkmcnt(8)
	v_mfma_f32_32x32x16_bf16 v[18:33], v[34:37], v[78:81], v[18:33]
	v_add_f32_e32 v238, v82, v195
	v_add_f32_e32 v239, v84, v196
	v_add_f32_e32 v240, v83, v85
	v_add_f32_e32 v241, v86, v87
	v_add_f32_e32 v238, v238, v239
	v_add_f32_e32 v240, v240, v241
	v_mfma_f32_32x32x16_bf16 v[2:17], v[34:37], v[74:77], v[2:17]
	v_max_f32_e32 v34, v114, v115
	v_max3_f32 v35, v116, v117, v99
	v_max3_f32 v34, v34, v98, v100
	v_max3_f32 v35, v35, v118, v119
	v_mfma_f32_32x32x16_bf16 v[18:33], v[42:45], v[70:73], v[18:33]
	v_max3_f32 v34, v34, v101, v120
	v_max3_f32 v35, v35, v102, v103
	v_add_f32_e32 v238, v240, v238
	v_add_f32_e32 v239, v88, v89
	v_add_f32_e32 v241, v90, v91
	v_mfma_f32_32x32x16_bf16 v[2:17], v[42:45], v[66:69], v[2:17]
	v_max3_f32 v34, v34, v121, v104
	v_max3_f32 v34, v34, v105, v124
	v_max3_f32 v35, v35, v122, v123
	v_add_f32_e32 v239, v239, v241
	v_add_f32_e32 v240, v92, v93
	v_add_f32_e32 v241, v94, v95
	s_waitcnt lgkmcnt(0)
	v_mfma_f32_32x32x16_bf16 v[18:33], v[46:49], v[212:215], v[18:33]
	v_max3_f32 v34, v34, v125, v108
	v_max3_f32 v35, v35, v106, v107
	v_add_f32_e32 v238, v239, v238
	v_add_f32_e32 v240, v240, v241
	s_waitcnt vmcnt(3)
	v_add_u32_e32 v67, s69, v187
	ds_write_b128 v67, v[162:165]
	v_mfma_f32_32x32x16_bf16 v[2:17], v[46:49], v[216:219], v[2:17]
	v_max3_f32 v34, v34, v109, v128
	v_max3_f32 v35, v35, v126, v127
	v_add_f32_e32 v238, v240, v238
	v_add_f32_e32 v239, v96, v97
	v_add_f32_e32 v241, v197, v198
	s_waitcnt vmcnt(2)
	ds_write_b128 v188, v[166:169] offset:24576
	v_mfma_f32_32x32x16_bf16 v[18:33], v[38:41], v[220:223], v[18:33]
	v_max3_f32 v34, v34, v129, v112
	v_max3_f32 v35, v35, v110, v111
	v_add_f32_e32 v239, v239, v241
	v_add_f32_e32 v240, v199, v200
	v_add_f32_e32 v241, v201, v202
	v_add_f32_e32 v238, v239, v238
	v_add_f32_e32 v240, v240, v241
	v_mfma_f32_32x32x16_bf16 v[2:17], v[38:41], v[228:231], v[2:17]
	v_max3_f32 v34, v34, v113, v35
	v_cmp_lt_f32_e32 vcc, s35, v34
	v_add_f32_e32 v238, v240, v238
	v_add_f32_e32 v239, v203, v204
	v_add_f32_e32 v241, v205, v206
	v_add_f32_e32 v239, v239, v241
	v_add_f32_e32 v240, v207, v208
	v_add_f32_e32 v241, v209, v210
	v_add_f32_e32 v238, v239, v238
	v_add_f32_e32 v240, v240, v241
	v_add_f32_e32 v238, v240, v238
	v_add_f32_e32 v194, v194, v238
	s_cbranch_vccnz .Lmy_y272
